# rope_rewrite_token_major
# baseline (speedup 1.0000x reference)
.Lg1_noextra:
	s_mov_b32 s89, 0
	s_mov_b32 s95, s89
	s_lshl_b64 s[0:1], s[94:95], 9
	s_lshl_b64 s[74:75], s[88:89], 9
	v_writelane_b32 v254, s0, 1
	v_writelane_b32 v254, s1, 2
	s_mov_b64 s[12:13], exec
	s_add_u32 s14, s46, 0x3c00000
	s_addc_u32 s15, s47, 0
	s_add_u32 s18, s46, 0x4400000
	s_addc_u32 s19, s47, 0
	s_mov_b32 s5, 0xffff0000
	v_lshl_add_u32 v2, s94, 9, v210
	v_lshrrev_b32_e32 v3, 2, v2
	v_and_b32_e32 v4, 3, v2
	v_lshlrev_b32_e32 v3, 7, v3
	v_lshl_add_u32 v0, v4, 4, v3
	v_lshl_add_u32 v1, v4, 5, v3
	global_load_dwordx4 v[8:11], v1, s[14:15]
	global_load_dwordx4 v[12:15], v1, s[14:15] offset:16
	global_load_dwordx4 v[16:19], v1, s[18:19]
	global_load_dwordx4 v[20:23], v1, s[18:19] offset:16
	s_add_u32 s0, s92, 0x0
	s_addc_u32 s1, s93, 0
	global_load_dwordx4 v[24:27], v0, s[0:1]
	global_load_dwordx4 v[28:31], v0, s[0:1] offset:64
	s_add_u32 s0, s92, 0x800000
	s_addc_u32 s1, s93, 0
	global_load_dwordx4 v[32:35], v0, s[0:1]
	global_load_dwordx4 v[36:39], v0, s[0:1] offset:64
	s_add_u32 s0, s92, 0x1000000
	s_addc_u32 s1, s93, 0
	global_load_dwordx4 v[40:43], v0, s[0:1]
	global_load_dwordx4 v[44:47], v0, s[0:1] offset:64
	s_add_u32 s0, s92, 0x1800000
	s_addc_u32 s1, s93, 0
	global_load_dwordx4 v[48:51], v0, s[0:1]
	global_load_dwordx4 v[52:55], v0, s[0:1] offset:64
	s_add_u32 s0, s92, 0x2000000
	s_addc_u32 s1, s93, 0
	global_load_dwordx4 v[56:59], v0, s[0:1]
	global_load_dwordx4 v[60:63], v0, s[0:1] offset:64
	s_add_u32 s0, s92, 0x2800000
	s_addc_u32 s1, s93, 0
	global_load_dwordx4 v[64:67], v0, s[0:1]
	global_load_dwordx4 v[68:71], v0, s[0:1] offset:64
	s_add_u32 s0, s92, 0x3000000
	s_addc_u32 s1, s93, 0
	global_load_dwordx4 v[72:75], v0, s[0:1]
	global_load_dwordx4 v[76:79], v0, s[0:1] offset:64
	s_add_u32 s0, s92, 0x3800000
	s_addc_u32 s1, s93, 0
	global_load_dwordx4 v[80:83], v0, s[0:1]
	global_load_dwordx4 v[84:87], v0, s[0:1] offset:64
	s_add_u32 s0, s92, 0x6000000
	s_addc_u32 s1, s93, 0
	global_load_dwordx4 v[88:91], v0, s[0:1]
	global_load_dwordx4 v[92:95], v0, s[0:1] offset:64
	s_add_u32 s0, s92, 0x6800000
	s_addc_u32 s1, s93, 0
	global_load_dwordx4 v[96:99], v0, s[0:1]
	global_load_dwordx4 v[100:103], v0, s[0:1] offset:64
	s_add_u32 s0, s92, 0x7000000
	s_addc_u32 s1, s93, 0
	global_load_dwordx4 v[104:107], v0, s[0:1]
	global_load_dwordx4 v[108:111], v0, s[0:1] offset:64
	s_add_u32 s0, s92, 0x7800000
	s_addc_u32 s1, s93, 0
	global_load_dwordx4 v[112:115], v0, s[0:1]
	global_load_dwordx4 v[116:119], v0, s[0:1] offset:64
	s_waitcnt vmcnt(22)
	s_mov_b32 s4, 0x3e38aa3b
	v_lshlrev_b32_e32 v150, 16, v24
	v_lshlrev_b32_e32 v151, 16, v28
	v_mul_f32_e32 v134, v8, v150
	v_mul_f32_e32 v152, v16, v151
	v_mul_f32_e32 v142, v8, v151
	v_mul_f32_e32 v153, v16, v150
	v_sub_f32_e32 v134, v134, v152
	v_add_f32_e32 v142, v142, v153
	v_and_b32_e32 v150, s5, v24
	v_and_b32_e32 v151, s5, v28
	v_mul_f32_e32 v135, v9, v150
	v_mul_f32_e32 v152, v17, v151
	v_mul_f32_e32 v143, v9, v151
	v_mul_f32_e32 v153, v17, v150
	v_sub_f32_e32 v135, v135, v152
	v_add_f32_e32 v143, v143, v153
	v_lshlrev_b32_e32 v150, 16, v25
	v_lshlrev_b32_e32 v151, 16, v29
	v_mul_f32_e32 v136, v10, v150
	v_mul_f32_e32 v152, v18, v151
	v_mul_f32_e32 v144, v10, v151
	v_mul_f32_e32 v153, v18, v150
	v_sub_f32_e32 v136, v136, v152
	v_add_f32_e32 v144, v144, v153
	v_and_b32_e32 v150, s5, v25
	v_and_b32_e32 v151, s5, v29
	v_mul_f32_e32 v137, v11, v150
	v_mul_f32_e32 v152, v19, v151
	v_mul_f32_e32 v145, v11, v151
	v_mul_f32_e32 v153, v19, v150
	v_sub_f32_e32 v137, v137, v152
	v_add_f32_e32 v145, v145, v153
	v_lshlrev_b32_e32 v150, 16, v26
	v_lshlrev_b32_e32 v151, 16, v30
	v_mul_f32_e32 v138, v12, v150
	v_mul_f32_e32 v152, v20, v151
	v_mul_f32_e32 v146, v12, v151
	v_mul_f32_e32 v153, v20, v150
	v_sub_f32_e32 v138, v138, v152
	v_add_f32_e32 v146, v146, v153
	v_and_b32_e32 v150, s5, v26
	v_and_b32_e32 v151, s5, v30
	v_mul_f32_e32 v139, v13, v150
	v_mul_f32_e32 v152, v21, v151
	v_mul_f32_e32 v147, v13, v151
	v_mul_f32_e32 v153, v21, v150
	v_sub_f32_e32 v139, v139, v152
	v_add_f32_e32 v147, v147, v153
	v_lshlrev_b32_e32 v150, 16, v27
	v_lshlrev_b32_e32 v151, 16, v31
	v_mul_f32_e32 v140, v14, v150
	v_mul_f32_e32 v152, v22, v151
	v_mul_f32_e32 v148, v14, v151
	v_mul_f32_e32 v153, v22, v150
	v_sub_f32_e32 v140, v140, v152
	v_add_f32_e32 v148, v148, v153
	v_and_b32_e32 v150, s5, v27
	v_and_b32_e32 v151, s5, v31
	v_mul_f32_e32 v141, v15, v150
	v_mul_f32_e32 v152, v23, v151
	v_mul_f32_e32 v149, v15, v151
	v_mul_f32_e32 v153, v23, v150
	v_sub_f32_e32 v141, v141, v152
	v_add_f32_e32 v149, v149, v153
	v_mul_f32_e32 v134, s4, v134
	v_mul_f32_e32 v142, s4, v142
	v_mul_f32_e32 v135, s4, v135
	v_mul_f32_e32 v143, s4, v143
	v_mul_f32_e32 v136, s4, v136
	v_mul_f32_e32 v144, s4, v144
	v_mul_f32_e32 v137, s4, v137
	v_mul_f32_e32 v145, s4, v145
	v_mul_f32_e32 v138, s4, v138
	v_mul_f32_e32 v146, s4, v146
	v_mul_f32_e32 v139, s4, v139
	v_mul_f32_e32 v147, s4, v147
	v_mul_f32_e32 v140, s4, v140
	v_mul_f32_e32 v148, s4, v148
	v_mul_f32_e32 v141, s4, v141
	v_mul_f32_e32 v149, s4, v149
	v_cvt_pk_bf16_f32 v24, v134, v135
	v_cvt_pk_bf16_f32 v28, v142, v143
	v_cvt_pk_bf16_f32 v25, v136, v137
	v_cvt_pk_bf16_f32 v29, v144, v145
	v_cvt_pk_bf16_f32 v26, v138, v139
	v_cvt_pk_bf16_f32 v30, v146, v147
	v_cvt_pk_bf16_f32 v27, v140, v141
	v_cvt_pk_bf16_f32 v31, v148, v149
	s_add_u32 s0, s92, 0x0
	s_addc_u32 s1, s93, 0
	global_store_dwordx4 v0, v[24:27], s[0:1]
	global_store_dwordx4 v0, v[28:31], s[0:1] offset:64
	s_waitcnt vmcnt(22)
	v_lshlrev_b32_e32 v150, 16, v32
	v_lshlrev_b32_e32 v151, 16, v36
	v_mul_f32_e32 v152, v16, v151
	v_mul_f32_e32 v142, v16, v150
	v_fma_f32 v134, v8, v150, -v152
	v_fmac_f32_e32 v142, v8, v151
	v_and_b32_e32 v150, s5, v32
	v_and_b32_e32 v151, s5, v36
	v_mul_f32_e32 v152, v17, v151
	v_mul_f32_e32 v143, v17, v150
	v_fma_f32 v135, v9, v150, -v152
	v_fmac_f32_e32 v143, v9, v151
	v_lshlrev_b32_e32 v150, 16, v33
	v_lshlrev_b32_e32 v151, 16, v37
	v_mul_f32_e32 v152, v18, v151
	v_mul_f32_e32 v144, v18, v150
	v_fma_f32 v136, v10, v150, -v152
	v_fmac_f32_e32 v144, v10, v151
	v_and_b32_e32 v150, s5, v33
	v_and_b32_e32 v151, s5, v37
	v_mul_f32_e32 v152, v19, v151
	v_mul_f32_e32 v145, v19, v150
	v_fma_f32 v137, v11, v150, -v152
	v_fmac_f32_e32 v145, v11, v151
	v_lshlrev_b32_e32 v150, 16, v34
	v_lshlrev_b32_e32 v151, 16, v38
	v_mul_f32_e32 v152, v20, v151
	v_mul_f32_e32 v146, v20, v150
	v_fma_f32 v138, v12, v150, -v152
	v_fmac_f32_e32 v146, v12, v151
	v_and_b32_e32 v150, s5, v34
	v_and_b32_e32 v151, s5, v38
	v_mul_f32_e32 v152, v21, v151
	v_mul_f32_e32 v147, v21, v150
	v_fma_f32 v139, v13, v150, -v152
	v_fmac_f32_e32 v147, v13, v151
	v_lshlrev_b32_e32 v150, 16, v35
	v_lshlrev_b32_e32 v151, 16, v39
	v_mul_f32_e32 v152, v22, v151
	v_mul_f32_e32 v148, v22, v150
	v_fma_f32 v140, v14, v150, -v152
	v_fmac_f32_e32 v148, v14, v151
	v_and_b32_e32 v150, s5, v35
	v_and_b32_e32 v151, s5, v39
	v_mul_f32_e32 v152, v23, v151
	v_mul_f32_e32 v149, v23, v150
	v_fma_f32 v141, v15, v150, -v152
	v_fmac_f32_e32 v149, v15, v151
	v_mul_f32_e32 v134, s4, v134
	v_mul_f32_e32 v142, s4, v142
	v_mul_f32_e32 v135, s4, v135
	v_mul_f32_e32 v143, s4, v143
	v_mul_f32_e32 v136, s4, v136
	v_mul_f32_e32 v144, s4, v144
	v_mul_f32_e32 v137, s4, v137
	v_mul_f32_e32 v145, s4, v145
	v_mul_f32_e32 v138, s4, v138
	v_mul_f32_e32 v146, s4, v146
	v_mul_f32_e32 v139, s4, v139
	v_mul_f32_e32 v147, s4, v147
	v_mul_f32_e32 v140, s4, v140
	v_mul_f32_e32 v148, s4, v148
	v_mul_f32_e32 v141, s4, v141
	v_mul_f32_e32 v149, s4, v149
	v_cvt_pk_bf16_f32 v32, v134, v135
	v_cvt_pk_bf16_f32 v36, v142, v143
	v_cvt_pk_bf16_f32 v33, v136, v137
	v_cvt_pk_bf16_f32 v37, v144, v145
	v_cvt_pk_bf16_f32 v34, v138, v139
	v_cvt_pk_bf16_f32 v38, v146, v147
	v_cvt_pk_bf16_f32 v35, v140, v141
	v_cvt_pk_bf16_f32 v39, v148, v149
	s_add_u32 s0, s92, 0x800000
	s_addc_u32 s1, s93, 0
	global_store_dwordx4 v0, v[32:35], s[0:1]
	global_store_dwordx4 v0, v[36:39], s[0:1] offset:64
	s_waitcnt vmcnt(22)
	v_lshlrev_b32_e32 v150, 16, v40
	v_lshlrev_b32_e32 v151, 16, v44
	v_mul_f32_e32 v134, v8, v150
	v_mul_f32_e32 v152, v16, v151
	v_mul_f32_e32 v142, v8, v151
	v_mul_f32_e32 v153, v16, v150
	v_sub_f32_e32 v134, v134, v152
	v_add_f32_e32 v142, v142, v153
	v_and_b32_e32 v150, s5, v40
	v_and_b32_e32 v151, s5, v44
	v_mul_f32_e32 v135, v9, v150
	v_mul_f32_e32 v152, v17, v151
	v_mul_f32_e32 v143, v9, v151
	v_mul_f32_e32 v153, v17, v150
	v_sub_f32_e32 v135, v135, v152
	v_add_f32_e32 v143, v143, v153
	v_lshlrev_b32_e32 v150, 16, v41
	v_lshlrev_b32_e32 v151, 16, v45
	v_mul_f32_e32 v136, v10, v150
	v_mul_f32_e32 v152, v18, v151
	v_mul_f32_e32 v144, v10, v151
	v_mul_f32_e32 v153, v18, v150
	v_sub_f32_e32 v136, v136, v152
	v_add_f32_e32 v144, v144, v153
	v_and_b32_e32 v150, s5, v41
	v_and_b32_e32 v151, s5, v45
	v_mul_f32_e32 v137, v11, v150
	v_mul_f32_e32 v152, v19, v151
	v_mul_f32_e32 v145, v11, v151
	v_mul_f32_e32 v153, v19, v150
	v_sub_f32_e32 v137, v137, v152
	v_add_f32_e32 v145, v145, v153
	v_lshlrev_b32_e32 v150, 16, v42
	v_lshlrev_b32_e32 v151, 16, v46
	v_mul_f32_e32 v138, v12, v150
	v_mul_f32_e32 v152, v20, v151
	v_mul_f32_e32 v146, v12, v151
	v_mul_f32_e32 v153, v20, v150
	v_sub_f32_e32 v138, v138, v152
	v_add_f32_e32 v146, v146, v153
	v_and_b32_e32 v150, s5, v42
	v_and_b32_e32 v151, s5, v46
	v_mul_f32_e32 v139, v13, v150
	v_mul_f32_e32 v152, v21, v151
	v_mul_f32_e32 v147, v13, v151
	v_mul_f32_e32 v153, v21, v150
	v_sub_f32_e32 v139, v139, v152
	v_add_f32_e32 v147, v147, v153
	v_lshlrev_b32_e32 v150, 16, v43
	v_lshlrev_b32_e32 v151, 16, v47
	v_mul_f32_e32 v140, v14, v150
	v_mul_f32_e32 v152, v22, v151
	v_mul_f32_e32 v148, v14, v151
	v_mul_f32_e32 v153, v22, v150
	v_sub_f32_e32 v140, v140, v152
	v_add_f32_e32 v148, v148, v153
	v_and_b32_e32 v150, s5, v43
	v_and_b32_e32 v151, s5, v47
	v_mul_f32_e32 v141, v15, v150
	v_mul_f32_e32 v152, v23, v151
	v_mul_f32_e32 v149, v15, v151
	v_mul_f32_e32 v153, v23, v150
	v_sub_f32_e32 v141, v141, v152
	v_add_f32_e32 v149, v149, v153
	v_mul_f32_e32 v134, s4, v134
	v_mul_f32_e32 v142, s4, v142
	v_mul_f32_e32 v135, s4, v135
	v_mul_f32_e32 v143, s4, v143
	v_mul_f32_e32 v136, s4, v136
	v_mul_f32_e32 v144, s4, v144
	v_mul_f32_e32 v137, s4, v137
	v_mul_f32_e32 v145, s4, v145
	v_mul_f32_e32 v138, s4, v138
	v_mul_f32_e32 v146, s4, v146
	v_mul_f32_e32 v139, s4, v139
	v_mul_f32_e32 v147, s4, v147
	v_mul_f32_e32 v140, s4, v140
	v_mul_f32_e32 v148, s4, v148
	v_mul_f32_e32 v141, s4, v141
	v_mul_f32_e32 v149, s4, v149
	v_cvt_pk_bf16_f32 v40, v134, v135
	v_cvt_pk_bf16_f32 v44, v142, v143
	v_cvt_pk_bf16_f32 v41, v136, v137
	v_cvt_pk_bf16_f32 v45, v144, v145
	v_cvt_pk_bf16_f32 v42, v138, v139
	v_cvt_pk_bf16_f32 v46, v146, v147
	v_cvt_pk_bf16_f32 v43, v140, v141
	v_cvt_pk_bf16_f32 v47, v148, v149
	s_add_u32 s0, s92, 0x1000000
	s_addc_u32 s1, s93, 0
	global_store_dwordx4 v0, v[40:43], s[0:1]
	global_store_dwordx4 v0, v[44:47], s[0:1] offset:64
	s_waitcnt vmcnt(22)
	v_lshlrev_b32_e32 v150, 16, v48
	v_lshlrev_b32_e32 v151, 16, v52
	v_mul_f32_e32 v152, v16, v151
	v_mul_f32_e32 v142, v16, v150
	v_fma_f32 v134, v8, v150, -v152
	v_fmac_f32_e32 v142, v8, v151
	v_and_b32_e32 v150, s5, v48
	v_and_b32_e32 v151, s5, v52
	v_mul_f32_e32 v152, v17, v151
	v_mul_f32_e32 v143, v17, v150
	v_fma_f32 v135, v9, v150, -v152
	v_fmac_f32_e32 v143, v9, v151
	v_lshlrev_b32_e32 v150, 16, v49
	v_lshlrev_b32_e32 v151, 16, v53
	v_mul_f32_e32 v152, v18, v151
	v_mul_f32_e32 v144, v18, v150
	v_fma_f32 v136, v10, v150, -v152
	v_fmac_f32_e32 v144, v10, v151
	v_and_b32_e32 v150, s5, v49
	v_and_b32_e32 v151, s5, v53
	v_mul_f32_e32 v152, v19, v151
	v_mul_f32_e32 v145, v19, v150
	v_fma_f32 v137, v11, v150, -v152
	v_fmac_f32_e32 v145, v11, v151
	v_lshlrev_b32_e32 v150, 16, v50
	v_lshlrev_b32_e32 v151, 16, v54
	v_mul_f32_e32 v152, v20, v151
	v_mul_f32_e32 v146, v20, v150
	v_fma_f32 v138, v12, v150, -v152
	v_fmac_f32_e32 v146, v12, v151
	v_and_b32_e32 v150, s5, v50
	v_and_b32_e32 v151, s5, v54
	v_mul_f32_e32 v152, v21, v151
	v_mul_f32_e32 v147, v21, v150
	v_fma_f32 v139, v13, v150, -v152
	v_fmac_f32_e32 v147, v13, v151
	v_lshlrev_b32_e32 v150, 16, v51
	v_lshlrev_b32_e32 v151, 16, v55
	v_mul_f32_e32 v152, v22, v151
	v_mul_f32_e32 v148, v22, v150
	v_fma_f32 v140, v14, v150, -v152
	v_fmac_f32_e32 v148, v14, v151
	v_and_b32_e32 v150, s5, v51
	v_and_b32_e32 v151, s5, v55
	v_mul_f32_e32 v152, v23, v151
	v_mul_f32_e32 v149, v23, v150
	v_fma_f32 v141, v15, v150, -v152
	v_fmac_f32_e32 v149, v15, v151
	v_mul_f32_e32 v134, s4, v134
	v_mul_f32_e32 v142, s4, v142
	v_mul_f32_e32 v135, s4, v135
	v_mul_f32_e32 v143, s4, v143
	v_mul_f32_e32 v136, s4, v136
	v_mul_f32_e32 v144, s4, v144
	v_mul_f32_e32 v137, s4, v137
	v_mul_f32_e32 v145, s4, v145
	v_mul_f32_e32 v138, s4, v138
	v_mul_f32_e32 v146, s4, v146
	v_mul_f32_e32 v139, s4, v139
	v_mul_f32_e32 v147, s4, v147
	v_mul_f32_e32 v140, s4, v140
	v_mul_f32_e32 v148, s4, v148
	v_mul_f32_e32 v141, s4, v141
	v_mul_f32_e32 v149, s4, v149
	v_cvt_pk_bf16_f32 v48, v134, v135
	v_cvt_pk_bf16_f32 v52, v142, v143
	v_cvt_pk_bf16_f32 v49, v136, v137
	v_cvt_pk_bf16_f32 v53, v144, v145
	v_cvt_pk_bf16_f32 v50, v138, v139
	v_cvt_pk_bf16_f32 v54, v146, v147
	v_cvt_pk_bf16_f32 v51, v140, v141
	v_cvt_pk_bf16_f32 v55, v148, v149
	s_add_u32 s0, s92, 0x1800000
	s_addc_u32 s1, s93, 0
	global_store_dwordx4 v0, v[48:51], s[0:1]
	global_store_dwordx4 v0, v[52:55], s[0:1] offset:64
	s_waitcnt vmcnt(22)
	v_lshlrev_b32_e32 v150, 16, v56
	v_lshlrev_b32_e32 v151, 16, v60
	v_mul_f32_e32 v134, v8, v150
	v_mul_f32_e32 v152, v16, v151
	v_mul_f32_e32 v142, v8, v151
	v_mul_f32_e32 v153, v16, v150
	v_sub_f32_e32 v134, v134, v152
	v_add_f32_e32 v142, v142, v153
	v_and_b32_e32 v150, s5, v56
	v_and_b32_e32 v151, s5, v60
	v_mul_f32_e32 v135, v9, v150
	v_mul_f32_e32 v152, v17, v151
	v_mul_f32_e32 v143, v9, v151
	v_mul_f32_e32 v153, v17, v150
	v_sub_f32_e32 v135, v135, v152
	v_add_f32_e32 v143, v143, v153
	v_lshlrev_b32_e32 v150, 16, v57
	v_lshlrev_b32_e32 v151, 16, v61
	v_mul_f32_e32 v136, v10, v150
	v_mul_f32_e32 v152, v18, v151
	v_mul_f32_e32 v144, v10, v151
	v_mul_f32_e32 v153, v18, v150
	v_sub_f32_e32 v136, v136, v152
	v_add_f32_e32 v144, v144, v153
	v_and_b32_e32 v150, s5, v57
	v_and_b32_e32 v151, s5, v61
	v_mul_f32_e32 v137, v11, v150
	v_mul_f32_e32 v152, v19, v151
	v_mul_f32_e32 v145, v11, v151
	v_mul_f32_e32 v153, v19, v150
	v_sub_f32_e32 v137, v137, v152
	v_add_f32_e32 v145, v145, v153
	v_lshlrev_b32_e32 v150, 16, v58
	v_lshlrev_b32_e32 v151, 16, v62
	v_mul_f32_e32 v138, v12, v150
	v_mul_f32_e32 v152, v20, v151
	v_mul_f32_e32 v146, v12, v151
	v_mul_f32_e32 v153, v20, v150
	v_sub_f32_e32 v138, v138, v152
	v_add_f32_e32 v146, v146, v153
	v_and_b32_e32 v150, s5, v58
	v_and_b32_e32 v151, s5, v62
	v_mul_f32_e32 v139, v13, v150
	v_mul_f32_e32 v152, v21, v151
	v_mul_f32_e32 v147, v13, v151
	v_mul_f32_e32 v153, v21, v150
	v_sub_f32_e32 v139, v139, v152
	v_add_f32_e32 v147, v147, v153
	v_lshlrev_b32_e32 v150, 16, v59
	v_lshlrev_b32_e32 v151, 16, v63
	v_mul_f32_e32 v140, v14, v150
	v_mul_f32_e32 v152, v22, v151
	v_mul_f32_e32 v148, v14, v151
	v_mul_f32_e32 v153, v22, v150
	v_sub_f32_e32 v140, v140, v152
	v_add_f32_e32 v148, v148, v153
	v_and_b32_e32 v150, s5, v59
	v_and_b32_e32 v151, s5, v63
	v_mul_f32_e32 v141, v15, v150
	v_mul_f32_e32 v152, v23, v151
	v_mul_f32_e32 v149, v15, v151
	v_mul_f32_e32 v153, v23, v150
	v_sub_f32_e32 v141, v141, v152
	v_add_f32_e32 v149, v149, v153
	v_mul_f32_e32 v134, s4, v134
	v_mul_f32_e32 v142, s4, v142
	v_mul_f32_e32 v135, s4, v135
	v_mul_f32_e32 v143, s4, v143
	v_mul_f32_e32 v136, s4, v136
	v_mul_f32_e32 v144, s4, v144
	v_mul_f32_e32 v137, s4, v137
	v_mul_f32_e32 v145, s4, v145
	v_mul_f32_e32 v138, s4, v138
	v_mul_f32_e32 v146, s4, v146
	v_mul_f32_e32 v139, s4, v139
	v_mul_f32_e32 v147, s4, v147
	v_mul_f32_e32 v140, s4, v140
	v_mul_f32_e32 v148, s4, v148
	v_mul_f32_e32 v141, s4, v141
	v_mul_f32_e32 v149, s4, v149
	v_cvt_pk_bf16_f32 v56, v134, v135
	v_cvt_pk_bf16_f32 v60, v142, v143
	v_cvt_pk_bf16_f32 v57, v136, v137
	v_cvt_pk_bf16_f32 v61, v144, v145
	v_cvt_pk_bf16_f32 v58, v138, v139
	v_cvt_pk_bf16_f32 v62, v146, v147
	v_cvt_pk_bf16_f32 v59, v140, v141
	v_cvt_pk_bf16_f32 v63, v148, v149
	s_add_u32 s0, s92, 0x2000000
	s_addc_u32 s1, s93, 0
	global_store_dwordx4 v0, v[56:59], s[0:1]
	global_store_dwordx4 v0, v[60:63], s[0:1] offset:64
	s_waitcnt vmcnt(22)
	v_lshlrev_b32_e32 v150, 16, v64
	v_lshlrev_b32_e32 v151, 16, v68
	v_mul_f32_e32 v152, v16, v151
	v_mul_f32_e32 v142, v16, v150
	v_fma_f32 v134, v8, v150, -v152
	v_fmac_f32_e32 v142, v8, v151
	v_and_b32_e32 v150, s5, v64
	v_and_b32_e32 v151, s5, v68
	v_mul_f32_e32 v152, v17, v151
	v_mul_f32_e32 v143, v17, v150
	v_fma_f32 v135, v9, v150, -v152
	v_fmac_f32_e32 v143, v9, v151
	v_lshlrev_b32_e32 v150, 16, v65
	v_lshlrev_b32_e32 v151, 16, v69
	v_mul_f32_e32 v152, v18, v151
	v_mul_f32_e32 v144, v18, v150
	v_fma_f32 v136, v10, v150, -v152
	v_fmac_f32_e32 v144, v10, v151
	v_and_b32_e32 v150, s5, v65
	v_and_b32_e32 v151, s5, v69
	v_mul_f32_e32 v152, v19, v151
	v_mul_f32_e32 v145, v19, v150
	v_fma_f32 v137, v11, v150, -v152
	v_fmac_f32_e32 v145, v11, v151
	v_lshlrev_b32_e32 v150, 16, v66
	v_lshlrev_b32_e32 v151, 16, v70
	v_mul_f32_e32 v152, v20, v151
	v_mul_f32_e32 v146, v20, v150
	v_fma_f32 v138, v12, v150, -v152
	v_fmac_f32_e32 v146, v12, v151
	v_and_b32_e32 v150, s5, v66
	v_and_b32_e32 v151, s5, v70
	v_mul_f32_e32 v152, v21, v151
	v_mul_f32_e32 v147, v21, v150
	v_fma_f32 v139, v13, v150, -v152
	v_fmac_f32_e32 v147, v13, v151
	v_lshlrev_b32_e32 v150, 16, v67
	v_lshlrev_b32_e32 v151, 16, v71
	v_mul_f32_e32 v152, v22, v151
	v_mul_f32_e32 v148, v22, v150
	v_fma_f32 v140, v14, v150, -v152
	v_fmac_f32_e32 v148, v14, v151
	v_and_b32_e32 v150, s5, v67
	v_and_b32_e32 v151, s5, v71
	v_mul_f32_e32 v152, v23, v151
	v_mul_f32_e32 v149, v23, v150
	v_fma_f32 v141, v15, v150, -v152
	v_fmac_f32_e32 v149, v15, v151
	v_mul_f32_e32 v134, s4, v134
	v_mul_f32_e32 v142, s4, v142
	v_mul_f32_e32 v135, s4, v135
	v_mul_f32_e32 v143, s4, v143
	v_mul_f32_e32 v136, s4, v136
	v_mul_f32_e32 v144, s4, v144
	v_mul_f32_e32 v137, s4, v137
	v_mul_f32_e32 v145, s4, v145
	v_mul_f32_e32 v138, s4, v138
	v_mul_f32_e32 v146, s4, v146
	v_mul_f32_e32 v139, s4, v139
	v_mul_f32_e32 v147, s4, v147
	v_mul_f32_e32 v140, s4, v140
	v_mul_f32_e32 v148, s4, v148
	v_mul_f32_e32 v141, s4, v141
	v_mul_f32_e32 v149, s4, v149
	v_cvt_pk_bf16_f32 v64, v134, v135
	v_cvt_pk_bf16_f32 v68, v142, v143
	v_cvt_pk_bf16_f32 v65, v136, v137
	v_cvt_pk_bf16_f32 v69, v144, v145
	v_cvt_pk_bf16_f32 v66, v138, v139
	v_cvt_pk_bf16_f32 v70, v146, v147
	v_cvt_pk_bf16_f32 v67, v140, v141
	v_cvt_pk_bf16_f32 v71, v148, v149
	s_add_u32 s0, s92, 0x2800000
	s_addc_u32 s1, s93, 0
	global_store_dwordx4 v0, v[64:67], s[0:1]
	global_store_dwordx4 v0, v[68:71], s[0:1] offset:64
	s_waitcnt vmcnt(22)
	v_lshlrev_b32_e32 v150, 16, v72
	v_lshlrev_b32_e32 v151, 16, v76
	v_mul_f32_e32 v134, v8, v150
	v_mul_f32_e32 v152, v16, v151
	v_mul_f32_e32 v142, v8, v151
	v_mul_f32_e32 v153, v16, v150
	v_sub_f32_e32 v134, v134, v152
	v_add_f32_e32 v142, v142, v153
	v_and_b32_e32 v150, s5, v72
	v_and_b32_e32 v151, s5, v76
	v_mul_f32_e32 v135, v9, v150
	v_mul_f32_e32 v152, v17, v151
	v_mul_f32_e32 v143, v9, v151
	v_mul_f32_e32 v153, v17, v150
	v_sub_f32_e32 v135, v135, v152
	v_add_f32_e32 v143, v143, v153
	v_lshlrev_b32_e32 v150, 16, v73
	v_lshlrev_b32_e32 v151, 16, v77
	v_mul_f32_e32 v136, v10, v150
	v_mul_f32_e32 v152, v18, v151
	v_mul_f32_e32 v144, v10, v151
	v_mul_f32_e32 v153, v18, v150
	v_sub_f32_e32 v136, v136, v152
	v_add_f32_e32 v144, v144, v153
	v_and_b32_e32 v150, s5, v73
	v_and_b32_e32 v151, s5, v77
	v_mul_f32_e32 v137, v11, v150
	v_mul_f32_e32 v152, v19, v151
	v_mul_f32_e32 v145, v11, v151
	v_mul_f32_e32 v153, v19, v150
	v_sub_f32_e32 v137, v137, v152
	v_add_f32_e32 v145, v145, v153
	v_lshlrev_b32_e32 v150, 16, v74
	v_lshlrev_b32_e32 v151, 16, v78
	v_mul_f32_e32 v138, v12, v150
	v_mul_f32_e32 v152, v20, v151
	v_mul_f32_e32 v146, v12, v151
	v_mul_f32_e32 v153, v20, v150
	v_sub_f32_e32 v138, v138, v152
	v_add_f32_e32 v146, v146, v153
	v_and_b32_e32 v150, s5, v74
	v_and_b32_e32 v151, s5, v78
	v_mul_f32_e32 v139, v13, v150
	v_mul_f32_e32 v152, v21, v151
	v_mul_f32_e32 v147, v13, v151
	v_mul_f32_e32 v153, v21, v150
	v_sub_f32_e32 v139, v139, v152
	v_add_f32_e32 v147, v147, v153
	v_lshlrev_b32_e32 v150, 16, v75
	v_lshlrev_b32_e32 v151, 16, v79
	v_mul_f32_e32 v140, v14, v150
	v_mul_f32_e32 v152, v22, v151
	v_mul_f32_e32 v148, v14, v151
	v_mul_f32_e32 v153, v22, v150
	v_sub_f32_e32 v140, v140, v152
	v_add_f32_e32 v148, v148, v153
	v_and_b32_e32 v150, s5, v75
	v_and_b32_e32 v151, s5, v79
	v_mul_f32_e32 v141, v15, v150
	v_mul_f32_e32 v152, v23, v151
	v_mul_f32_e32 v149, v15, v151
	v_mul_f32_e32 v153, v23, v150
	v_sub_f32_e32 v141, v141, v152
	v_add_f32_e32 v149, v149, v153
	v_mul_f32_e32 v134, s4, v134
	v_mul_f32_e32 v142, s4, v142
	v_mul_f32_e32 v135, s4, v135
	v_mul_f32_e32 v143, s4, v143
	v_mul_f32_e32 v136, s4, v136
	v_mul_f32_e32 v144, s4, v144
	v_mul_f32_e32 v137, s4, v137
	v_mul_f32_e32 v145, s4, v145
	v_mul_f32_e32 v138, s4, v138
	v_mul_f32_e32 v146, s4, v146
	v_mul_f32_e32 v139, s4, v139
	v_mul_f32_e32 v147, s4, v147
	v_mul_f32_e32 v140, s4, v140
	v_mul_f32_e32 v148, s4, v148
	v_mul_f32_e32 v141, s4, v141
	v_mul_f32_e32 v149, s4, v149
	v_cvt_pk_bf16_f32 v72, v134, v135
	v_cvt_pk_bf16_f32 v76, v142, v143
	v_cvt_pk_bf16_f32 v73, v136, v137
	v_cvt_pk_bf16_f32 v77, v144, v145
	v_cvt_pk_bf16_f32 v74, v138, v139
	v_cvt_pk_bf16_f32 v78, v146, v147
	v_cvt_pk_bf16_f32 v75, v140, v141
	v_cvt_pk_bf16_f32 v79, v148, v149
	s_add_u32 s0, s92, 0x3000000
	s_addc_u32 s1, s93, 0
	global_store_dwordx4 v0, v[72:75], s[0:1]
	global_store_dwordx4 v0, v[76:79], s[0:1] offset:64
	s_waitcnt vmcnt(22)
	v_lshlrev_b32_e32 v150, 16, v80
	v_lshlrev_b32_e32 v151, 16, v84
	v_mul_f32_e32 v152, v16, v151
	v_mul_f32_e32 v142, v16, v150
	v_fma_f32 v134, v8, v150, -v152
	v_fmac_f32_e32 v142, v8, v151
	v_and_b32_e32 v150, s5, v80
	v_and_b32_e32 v151, s5, v84
	v_mul_f32_e32 v152, v17, v151
	v_mul_f32_e32 v143, v17, v150
	v_fma_f32 v135, v9, v150, -v152
	v_fmac_f32_e32 v143, v9, v151
	v_lshlrev_b32_e32 v150, 16, v81
	v_lshlrev_b32_e32 v151, 16, v85
	v_mul_f32_e32 v152, v18, v151
	v_mul_f32_e32 v144, v18, v150
	v_fma_f32 v136, v10, v150, -v152
	v_fmac_f32_e32 v144, v10, v151
	v_and_b32_e32 v150, s5, v81
	v_and_b32_e32 v151, s5, v85
	v_mul_f32_e32 v152, v19, v151
	v_mul_f32_e32 v145, v19, v150
	v_fma_f32 v137, v11, v150, -v152
	v_fmac_f32_e32 v145, v11, v151
	v_lshlrev_b32_e32 v150, 16, v82
	v_lshlrev_b32_e32 v151, 16, v86
	v_mul_f32_e32 v152, v20, v151
	v_mul_f32_e32 v146, v20, v150
	v_fma_f32 v138, v12, v150, -v152
	v_fmac_f32_e32 v146, v12, v151
	v_and_b32_e32 v150, s5, v82
	v_and_b32_e32 v151, s5, v86
	v_mul_f32_e32 v152, v21, v151
	v_mul_f32_e32 v147, v21, v150
	v_fma_f32 v139, v13, v150, -v152
	v_fmac_f32_e32 v147, v13, v151
	v_lshlrev_b32_e32 v150, 16, v83
	v_lshlrev_b32_e32 v151, 16, v87
	v_mul_f32_e32 v152, v22, v151
	v_mul_f32_e32 v148, v22, v150
	v_fma_f32 v140, v14, v150, -v152
	v_fmac_f32_e32 v148, v14, v151
	v_and_b32_e32 v150, s5, v83
	v_and_b32_e32 v151, s5, v87
	v_mul_f32_e32 v152, v23, v151
	v_mul_f32_e32 v149, v23, v150
	v_fma_f32 v141, v15, v150, -v152
	v_fmac_f32_e32 v149, v15, v151
	v_mul_f32_e32 v134, s4, v134
	v_mul_f32_e32 v142, s4, v142
	v_mul_f32_e32 v135, s4, v135
	v_mul_f32_e32 v143, s4, v143
	v_mul_f32_e32 v136, s4, v136
	v_mul_f32_e32 v144, s4, v144
	v_mul_f32_e32 v137, s4, v137
	v_mul_f32_e32 v145, s4, v145
	v_mul_f32_e32 v138, s4, v138
	v_mul_f32_e32 v146, s4, v146
	v_mul_f32_e32 v139, s4, v139
	v_mul_f32_e32 v147, s4, v147
	v_mul_f32_e32 v140, s4, v140
	v_mul_f32_e32 v148, s4, v148
	v_mul_f32_e32 v141, s4, v141
	v_mul_f32_e32 v149, s4, v149
	v_cvt_pk_bf16_f32 v80, v134, v135
	v_cvt_pk_bf16_f32 v84, v142, v143
	v_cvt_pk_bf16_f32 v81, v136, v137
	v_cvt_pk_bf16_f32 v85, v144, v145
	v_cvt_pk_bf16_f32 v82, v138, v139
	v_cvt_pk_bf16_f32 v86, v146, v147
	v_cvt_pk_bf16_f32 v83, v140, v141
	v_cvt_pk_bf16_f32 v87, v148, v149
	s_add_u32 s0, s92, 0x3800000
	s_addc_u32 s1, s93, 0
	global_store_dwordx4 v0, v[80:83], s[0:1]
	global_store_dwordx4 v0, v[84:87], s[0:1] offset:64
	s_waitcnt vmcnt(22)
	s_mov_b32 s4, 1.0
	v_lshlrev_b32_e32 v150, 16, v88
	v_lshlrev_b32_e32 v151, 16, v92
	v_mul_f32_e32 v134, v8, v150
	v_mul_f32_e32 v152, v16, v151
	v_mul_f32_e32 v142, v8, v151
	v_mul_f32_e32 v153, v16, v150
	v_sub_f32_e32 v134, v134, v152
	v_add_f32_e32 v142, v142, v153
	v_and_b32_e32 v150, s5, v88
	v_and_b32_e32 v151, s5, v92
	v_mul_f32_e32 v135, v9, v150
	v_mul_f32_e32 v152, v17, v151
	v_mul_f32_e32 v143, v9, v151
	v_mul_f32_e32 v153, v17, v150
	v_sub_f32_e32 v135, v135, v152
	v_add_f32_e32 v143, v143, v153
	v_lshlrev_b32_e32 v150, 16, v89
	v_lshlrev_b32_e32 v151, 16, v93
	v_mul_f32_e32 v136, v10, v150
	v_mul_f32_e32 v152, v18, v151
	v_mul_f32_e32 v144, v10, v151
	v_mul_f32_e32 v153, v18, v150
	v_sub_f32_e32 v136, v136, v152
	v_add_f32_e32 v144, v144, v153
	v_and_b32_e32 v150, s5, v89
	v_and_b32_e32 v151, s5, v93
	v_mul_f32_e32 v137, v11, v150
	v_mul_f32_e32 v152, v19, v151
	v_mul_f32_e32 v145, v11, v151
	v_mul_f32_e32 v153, v19, v150
	v_sub_f32_e32 v137, v137, v152
	v_add_f32_e32 v145, v145, v153
	v_lshlrev_b32_e32 v150, 16, v90
	v_lshlrev_b32_e32 v151, 16, v94
	v_mul_f32_e32 v138, v12, v150
	v_mul_f32_e32 v152, v20, v151
	v_mul_f32_e32 v146, v12, v151
	v_mul_f32_e32 v153, v20, v150
	v_sub_f32_e32 v138, v138, v152
	v_add_f32_e32 v146, v146, v153
	v_and_b32_e32 v150, s5, v90
	v_and_b32_e32 v151, s5, v94
	v_mul_f32_e32 v139, v13, v150
	v_mul_f32_e32 v152, v21, v151
	v_mul_f32_e32 v147, v13, v151
	v_mul_f32_e32 v153, v21, v150
	v_sub_f32_e32 v139, v139, v152
	v_add_f32_e32 v147, v147, v153
	v_lshlrev_b32_e32 v150, 16, v91
	v_lshlrev_b32_e32 v151, 16, v95
	v_mul_f32_e32 v140, v14, v150
	v_mul_f32_e32 v152, v22, v151
	v_mul_f32_e32 v148, v14, v151
	v_mul_f32_e32 v153, v22, v150
	v_sub_f32_e32 v140, v140, v152
	v_add_f32_e32 v148, v148, v153
	v_and_b32_e32 v150, s5, v91
	v_and_b32_e32 v151, s5, v95
	v_mul_f32_e32 v141, v15, v150
	v_mul_f32_e32 v152, v23, v151
	v_mul_f32_e32 v149, v15, v151
	v_mul_f32_e32 v153, v23, v150
	v_sub_f32_e32 v141, v141, v152
	v_add_f32_e32 v149, v149, v153
	v_mul_f32_e32 v134, s4, v134
	v_mul_f32_e32 v142, s4, v142
	v_mul_f32_e32 v135, s4, v135
	v_mul_f32_e32 v143, s4, v143
	v_mul_f32_e32 v136, s4, v136
	v_mul_f32_e32 v144, s4, v144
	v_mul_f32_e32 v137, s4, v137
	v_mul_f32_e32 v145, s4, v145
	v_mul_f32_e32 v138, s4, v138
	v_mul_f32_e32 v146, s4, v146
	v_mul_f32_e32 v139, s4, v139
	v_mul_f32_e32 v147, s4, v147
	v_mul_f32_e32 v140, s4, v140
	v_mul_f32_e32 v148, s4, v148
	v_mul_f32_e32 v141, s4, v141
	v_mul_f32_e32 v149, s4, v149
	v_cvt_pk_bf16_f32 v88, v134, v135
	v_cvt_pk_bf16_f32 v92, v142, v143
	v_cvt_pk_bf16_f32 v89, v136, v137
	v_cvt_pk_bf16_f32 v93, v144, v145
	v_cvt_pk_bf16_f32 v90, v138, v139
	v_cvt_pk_bf16_f32 v94, v146, v147
	v_cvt_pk_bf16_f32 v91, v140, v141
	v_cvt_pk_bf16_f32 v95, v148, v149
	s_add_u32 s0, s92, 0x6000000
	s_addc_u32 s1, s93, 0
	global_store_dwordx4 v0, v[88:91], s[0:1]
	global_store_dwordx4 v0, v[92:95], s[0:1] offset:64
	s_waitcnt vmcnt(22)
	v_lshlrev_b32_e32 v150, 16, v96
	v_lshlrev_b32_e32 v151, 16, v100
	v_mul_f32_e32 v152, v16, v151
	v_mul_f32_e32 v142, v16, v150
	v_fma_f32 v134, v8, v150, -v152
	v_fmac_f32_e32 v142, v8, v151
	v_and_b32_e32 v150, s5, v96
	v_and_b32_e32 v151, s5, v100
	v_mul_f32_e32 v152, v17, v151
	v_mul_f32_e32 v143, v17, v150
	v_fma_f32 v135, v9, v150, -v152
	v_fmac_f32_e32 v143, v9, v151
	v_lshlrev_b32_e32 v150, 16, v97
	v_lshlrev_b32_e32 v151, 16, v101
	v_mul_f32_e32 v152, v18, v151
	v_mul_f32_e32 v144, v18, v150
	v_fma_f32 v136, v10, v150, -v152
	v_fmac_f32_e32 v144, v10, v151
	v_and_b32_e32 v150, s5, v97
	v_and_b32_e32 v151, s5, v101
	v_mul_f32_e32 v152, v19, v151
	v_mul_f32_e32 v145, v19, v150
	v_fma_f32 v137, v11, v150, -v152
	v_fmac_f32_e32 v145, v11, v151
	v_lshlrev_b32_e32 v150, 16, v98
	v_lshlrev_b32_e32 v151, 16, v102
	v_mul_f32_e32 v152, v20, v151
	v_mul_f32_e32 v146, v20, v150
	v_fma_f32 v138, v12, v150, -v152
	v_fmac_f32_e32 v146, v12, v151
	v_and_b32_e32 v150, s5, v98
	v_and_b32_e32 v151, s5, v102
	v_mul_f32_e32 v152, v21, v151
	v_mul_f32_e32 v147, v21, v150
	v_fma_f32 v139, v13, v150, -v152
	v_fmac_f32_e32 v147, v13, v151
	v_lshlrev_b32_e32 v150, 16, v99
	v_lshlrev_b32_e32 v151, 16, v103
	v_mul_f32_e32 v152, v22, v151
	v_mul_f32_e32 v148, v22, v150
	v_fma_f32 v140, v14, v150, -v152
	v_fmac_f32_e32 v148, v14, v151
	v_and_b32_e32 v150, s5, v99
	v_and_b32_e32 v151, s5, v103
	v_mul_f32_e32 v152, v23, v151
	v_mul_f32_e32 v149, v23, v150
	v_fma_f32 v141, v15, v150, -v152
	v_fmac_f32_e32 v149, v15, v151
	v_mul_f32_e32 v134, s4, v134
	v_mul_f32_e32 v142, s4, v142
	v_mul_f32_e32 v135, s4, v135
	v_mul_f32_e32 v143, s4, v143
	v_mul_f32_e32 v136, s4, v136
	v_mul_f32_e32 v144, s4, v144
	v_mul_f32_e32 v137, s4, v137
	v_mul_f32_e32 v145, s4, v145
	v_mul_f32_e32 v138, s4, v138
	v_mul_f32_e32 v146, s4, v146
	v_mul_f32_e32 v139, s4, v139
	v_mul_f32_e32 v147, s4, v147
	v_mul_f32_e32 v140, s4, v140
	v_mul_f32_e32 v148, s4, v148
	v_mul_f32_e32 v141, s4, v141
	v_mul_f32_e32 v149, s4, v149
	v_cvt_pk_bf16_f32 v96, v134, v135
	v_cvt_pk_bf16_f32 v100, v142, v143
	v_cvt_pk_bf16_f32 v97, v136, v137
	v_cvt_pk_bf16_f32 v101, v144, v145
	v_cvt_pk_bf16_f32 v98, v138, v139
	v_cvt_pk_bf16_f32 v102, v146, v147
	v_cvt_pk_bf16_f32 v99, v140, v141
	v_cvt_pk_bf16_f32 v103, v148, v149
	s_add_u32 s0, s92, 0x6800000
	s_addc_u32 s1, s93, 0
	global_store_dwordx4 v0, v[96:99], s[0:1]
	global_store_dwordx4 v0, v[100:103], s[0:1] offset:64
	s_waitcnt vmcnt(22)
	v_lshlrev_b32_e32 v150, 16, v104
	v_lshlrev_b32_e32 v151, 16, v108
	v_mul_f32_e32 v134, v8, v150
	v_mul_f32_e32 v152, v16, v151
	v_mul_f32_e32 v142, v8, v151
	v_mul_f32_e32 v153, v16, v150
	v_sub_f32_e32 v134, v134, v152
	v_add_f32_e32 v142, v142, v153
	v_and_b32_e32 v150, s5, v104
	v_and_b32_e32 v151, s5, v108
	v_mul_f32_e32 v135, v9, v150
	v_mul_f32_e32 v152, v17, v151
	v_mul_f32_e32 v143, v9, v151
	v_mul_f32_e32 v153, v17, v150
	v_sub_f32_e32 v135, v135, v152
	v_add_f32_e32 v143, v143, v153
	v_lshlrev_b32_e32 v150, 16, v105
	v_lshlrev_b32_e32 v151, 16, v109
	v_mul_f32_e32 v136, v10, v150
	v_mul_f32_e32 v152, v18, v151
	v_mul_f32_e32 v144, v10, v151
	v_mul_f32_e32 v153, v18, v150
	v_sub_f32_e32 v136, v136, v152
	v_add_f32_e32 v144, v144, v153
	v_and_b32_e32 v150, s5, v105
	v_and_b32_e32 v151, s5, v109
	v_mul_f32_e32 v137, v11, v150
	v_mul_f32_e32 v152, v19, v151
	v_mul_f32_e32 v145, v11, v151
	v_mul_f32_e32 v153, v19, v150
	v_sub_f32_e32 v137, v137, v152
	v_add_f32_e32 v145, v145, v153
	v_lshlrev_b32_e32 v150, 16, v106
	v_lshlrev_b32_e32 v151, 16, v110
	v_mul_f32_e32 v138, v12, v150
	v_mul_f32_e32 v152, v20, v151
	v_mul_f32_e32 v146, v12, v151
	v_mul_f32_e32 v153, v20, v150
	v_sub_f32_e32 v138, v138, v152
	v_add_f32_e32 v146, v146, v153
	v_and_b32_e32 v150, s5, v106
	v_and_b32_e32 v151, s5, v110
	v_mul_f32_e32 v139, v13, v150
	v_mul_f32_e32 v152, v21, v151
	v_mul_f32_e32 v147, v13, v151
	v_mul_f32_e32 v153, v21, v150
	v_sub_f32_e32 v139, v139, v152
	v_add_f32_e32 v147, v147, v153
	v_lshlrev_b32_e32 v150, 16, v107
	v_lshlrev_b32_e32 v151, 16, v111
	v_mul_f32_e32 v140, v14, v150
	v_mul_f32_e32 v152, v22, v151
	v_mul_f32_e32 v148, v14, v151
	v_mul_f32_e32 v153, v22, v150
	v_sub_f32_e32 v140, v140, v152
	v_add_f32_e32 v148, v148, v153
	v_and_b32_e32 v150, s5, v107
	v_and_b32_e32 v151, s5, v111
	v_mul_f32_e32 v141, v15, v150
	v_mul_f32_e32 v152, v23, v151
	v_mul_f32_e32 v149, v15, v151
	v_mul_f32_e32 v153, v23, v150
	v_sub_f32_e32 v141, v141, v152
	v_add_f32_e32 v149, v149, v153
	v_mul_f32_e32 v134, s4, v134
	v_mul_f32_e32 v142, s4, v142
	v_mul_f32_e32 v135, s4, v135
	v_mul_f32_e32 v143, s4, v143
	v_mul_f32_e32 v136, s4, v136
	v_mul_f32_e32 v144, s4, v144
	v_mul_f32_e32 v137, s4, v137
	v_mul_f32_e32 v145, s4, v145
	v_mul_f32_e32 v138, s4, v138
	v_mul_f32_e32 v146, s4, v146
	v_mul_f32_e32 v139, s4, v139
	v_mul_f32_e32 v147, s4, v147
	v_mul_f32_e32 v140, s4, v140
	v_mul_f32_e32 v148, s4, v148
	v_mul_f32_e32 v141, s4, v141
	v_mul_f32_e32 v149, s4, v149
	v_cvt_pk_bf16_f32 v104, v134, v135
	v_cvt_pk_bf16_f32 v108, v142, v143
	v_cvt_pk_bf16_f32 v105, v136, v137
	v_cvt_pk_bf16_f32 v109, v144, v145
	v_cvt_pk_bf16_f32 v106, v138, v139
	v_cvt_pk_bf16_f32 v110, v146, v147
	v_cvt_pk_bf16_f32 v107, v140, v141
	v_cvt_pk_bf16_f32 v111, v148, v149
	s_add_u32 s0, s92, 0x7000000
	s_addc_u32 s1, s93, 0
	global_store_dwordx4 v0, v[104:107], s[0:1]
	global_store_dwordx4 v0, v[108:111], s[0:1] offset:64
	s_waitcnt vmcnt(22)
	v_lshlrev_b32_e32 v150, 16, v112
	v_lshlrev_b32_e32 v151, 16, v116
	v_mul_f32_e32 v152, v16, v151
	v_mul_f32_e32 v142, v16, v150
	v_fma_f32 v134, v8, v150, -v152
	v_fmac_f32_e32 v142, v8, v151
	v_and_b32_e32 v150, s5, v112
	v_and_b32_e32 v151, s5, v116
	v_mul_f32_e32 v152, v17, v151
	v_mul_f32_e32 v143, v17, v150
	v_fma_f32 v135, v9, v150, -v152
	v_fmac_f32_e32 v143, v9, v151
	v_lshlrev_b32_e32 v150, 16, v113
	v_lshlrev_b32_e32 v151, 16, v117
	v_mul_f32_e32 v152, v18, v151
	v_mul_f32_e32 v144, v18, v150
	v_fma_f32 v136, v10, v150, -v152
	v_fmac_f32_e32 v144, v10, v151
	v_and_b32_e32 v150, s5, v113
	v_and_b32_e32 v151, s5, v117
	v_mul_f32_e32 v152, v19, v151
	v_mul_f32_e32 v145, v19, v150
	v_fma_f32 v137, v11, v150, -v152
	v_fmac_f32_e32 v145, v11, v151
	v_lshlrev_b32_e32 v150, 16, v114
	v_lshlrev_b32_e32 v151, 16, v118
	v_mul_f32_e32 v152, v20, v151
	v_mul_f32_e32 v146, v20, v150
	v_fma_f32 v138, v12, v150, -v152
	v_fmac_f32_e32 v146, v12, v151
	v_and_b32_e32 v150, s5, v114
	v_and_b32_e32 v151, s5, v118
	v_mul_f32_e32 v152, v21, v151
	v_mul_f32_e32 v147, v21, v150
	v_fma_f32 v139, v13, v150, -v152
	v_fmac_f32_e32 v147, v13, v151
	v_lshlrev_b32_e32 v150, 16, v115
	v_lshlrev_b32_e32 v151, 16, v119
	v_mul_f32_e32 v152, v22, v151
	v_mul_f32_e32 v148, v22, v150
	v_fma_f32 v140, v14, v150, -v152
	v_fmac_f32_e32 v148, v14, v151
	v_and_b32_e32 v150, s5, v115
	v_and_b32_e32 v151, s5, v119
	v_mul_f32_e32 v152, v23, v151
	v_mul_f32_e32 v149, v23, v150
	v_fma_f32 v141, v15, v150, -v152
	v_fmac_f32_e32 v149, v15, v151
	v_mul_f32_e32 v134, s4, v134
	v_mul_f32_e32 v142, s4, v142
	v_mul_f32_e32 v135, s4, v135
	v_mul_f32_e32 v143, s4, v143
	v_mul_f32_e32 v136, s4, v136
	v_mul_f32_e32 v144, s4, v144
	v_mul_f32_e32 v137, s4, v137
	v_mul_f32_e32 v145, s4, v145
	v_mul_f32_e32 v138, s4, v138
	v_mul_f32_e32 v146, s4, v146
	v_mul_f32_e32 v139, s4, v139
	v_mul_f32_e32 v147, s4, v147
	v_mul_f32_e32 v140, s4, v140
	v_mul_f32_e32 v148, s4, v148
	v_mul_f32_e32 v141, s4, v141
	v_mul_f32_e32 v149, s4, v149
	v_cvt_pk_bf16_f32 v112, v134, v135
	v_cvt_pk_bf16_f32 v116, v142, v143
	v_cvt_pk_bf16_f32 v113, v136, v137
	v_cvt_pk_bf16_f32 v117, v144, v145
	v_cvt_pk_bf16_f32 v114, v138, v139
	v_cvt_pk_bf16_f32 v118, v146, v147
	v_cvt_pk_bf16_f32 v115, v140, v141
	v_cvt_pk_bf16_f32 v119, v148, v149
	s_add_u32 s0, s92, 0x7800000
	s_addc_u32 s1, s93, 0
	global_store_dwordx4 v0, v[112:115], s[0:1]
	global_store_dwordx4 v0, v[116:119], s[0:1] offset:64
	v_add_u32_e32 v2, 0x20000, v2
	v_lshrrev_b32_e32 v3, 2, v2
	v_and_b32_e32 v4, 3, v2
	v_lshlrev_b32_e32 v3, 7, v3
	v_lshl_add_u32 v0, v4, 4, v3
	v_lshl_add_u32 v1, v4, 5, v3
	global_load_dwordx4 v[8:11], v1, s[14:15]
	global_load_dwordx4 v[12:15], v1, s[14:15] offset:16
	global_load_dwordx4 v[16:19], v1, s[18:19]
	global_load_dwordx4 v[20:23], v1, s[18:19] offset:16
	s_add_u32 s0, s92, 0x0
	s_addc_u32 s1, s93, 0
	global_load_dwordx4 v[24:27], v0, s[0:1]
	global_load_dwordx4 v[28:31], v0, s[0:1] offset:64
	s_add_u32 s0, s92, 0x800000
	s_addc_u32 s1, s93, 0
	global_load_dwordx4 v[32:35], v0, s[0:1]
	global_load_dwordx4 v[36:39], v0, s[0:1] offset:64
	s_add_u32 s0, s92, 0x1000000
	s_addc_u32 s1, s93, 0
	global_load_dwordx4 v[40:43], v0, s[0:1]
	global_load_dwordx4 v[44:47], v0, s[0:1] offset:64
	s_add_u32 s0, s92, 0x1800000
	s_addc_u32 s1, s93, 0
	global_load_dwordx4 v[48:51], v0, s[0:1]
	global_load_dwordx4 v[52:55], v0, s[0:1] offset:64
	s_add_u32 s0, s92, 0x2000000
	s_addc_u32 s1, s93, 0
	global_load_dwordx4 v[56:59], v0, s[0:1]
	global_load_dwordx4 v[60:63], v0, s[0:1] offset:64
	s_add_u32 s0, s92, 0x2800000
	s_addc_u32 s1, s93, 0
	global_load_dwordx4 v[64:67], v0, s[0:1]
	global_load_dwordx4 v[68:71], v0, s[0:1] offset:64
	s_add_u32 s0, s92, 0x3000000
	s_addc_u32 s1, s93, 0
	global_load_dwordx4 v[72:75], v0, s[0:1]
	global_load_dwordx4 v[76:79], v0, s[0:1] offset:64
	s_add_u32 s0, s92, 0x3800000
	s_addc_u32 s1, s93, 0
	global_load_dwordx4 v[80:83], v0, s[0:1]
	global_load_dwordx4 v[84:87], v0, s[0:1] offset:64
	s_add_u32 s0, s92, 0x6000000
	s_addc_u32 s1, s93, 0
	global_load_dwordx4 v[88:91], v0, s[0:1]
	global_load_dwordx4 v[92:95], v0, s[0:1] offset:64
	s_add_u32 s0, s92, 0x6800000
	s_addc_u32 s1, s93, 0
	global_load_dwordx4 v[96:99], v0, s[0:1]
	global_load_dwordx4 v[100:103], v0, s[0:1] offset:64
	s_add_u32 s0, s92, 0x7000000
	s_addc_u32 s1, s93, 0
	global_load_dwordx4 v[104:107], v0, s[0:1]
	global_load_dwordx4 v[108:111], v0, s[0:1] offset:64
	s_add_u32 s0, s92, 0x7800000
	s_addc_u32 s1, s93, 0
	global_load_dwordx4 v[112:115], v0, s[0:1]
	global_load_dwordx4 v[116:119], v0, s[0:1] offset:64
	s_waitcnt vmcnt(22)
	s_mov_b32 s4, 0x3e38aa3b
	v_lshlrev_b32_e32 v150, 16, v24
	v_lshlrev_b32_e32 v151, 16, v28
	v_mul_f32_e32 v152, v16, v151
	v_mul_f32_e32 v142, v16, v150
	v_fma_f32 v134, v8, v150, -v152
	v_fmac_f32_e32 v142, v8, v151
	v_and_b32_e32 v150, s5, v24
	v_and_b32_e32 v151, s5, v28
	v_mul_f32_e32 v152, v17, v151
	v_mul_f32_e32 v143, v17, v150
	v_fma_f32 v135, v9, v150, -v152
	v_fmac_f32_e32 v143, v9, v151
	v_lshlrev_b32_e32 v150, 16, v25
	v_lshlrev_b32_e32 v151, 16, v29
	v_mul_f32_e32 v152, v18, v151
	v_mul_f32_e32 v144, v18, v150
	v_fma_f32 v136, v10, v150, -v152
	v_fmac_f32_e32 v144, v10, v151
	v_and_b32_e32 v150, s5, v25
	v_and_b32_e32 v151, s5, v29
	v_mul_f32_e32 v152, v19, v151
	v_mul_f32_e32 v145, v19, v150
	v_fma_f32 v137, v11, v150, -v152
	v_fmac_f32_e32 v145, v11, v151
	v_lshlrev_b32_e32 v150, 16, v26
	v_lshlrev_b32_e32 v151, 16, v30
	v_mul_f32_e32 v152, v20, v151
	v_mul_f32_e32 v146, v20, v150
	v_fma_f32 v138, v12, v150, -v152
	v_fmac_f32_e32 v146, v12, v151
	v_and_b32_e32 v150, s5, v26
	v_and_b32_e32 v151, s5, v30
	v_mul_f32_e32 v152, v21, v151
	v_mul_f32_e32 v147, v21, v150
	v_fma_f32 v139, v13, v150, -v152
	v_fmac_f32_e32 v147, v13, v151
	v_lshlrev_b32_e32 v150, 16, v27
	v_lshlrev_b32_e32 v151, 16, v31
	v_mul_f32_e32 v152, v22, v151
	v_mul_f32_e32 v148, v22, v150
	v_fma_f32 v140, v14, v150, -v152
	v_fmac_f32_e32 v148, v14, v151
	v_and_b32_e32 v150, s5, v27
	v_and_b32_e32 v151, s5, v31
	v_mul_f32_e32 v152, v23, v151
	v_mul_f32_e32 v149, v23, v150
	v_fma_f32 v141, v15, v150, -v152
	v_fmac_f32_e32 v149, v15, v151
	v_mul_f32_e32 v134, s4, v134
	v_mul_f32_e32 v142, s4, v142
	v_mul_f32_e32 v135, s4, v135
	v_mul_f32_e32 v143, s4, v143
	v_mul_f32_e32 v136, s4, v136
	v_mul_f32_e32 v144, s4, v144
	v_mul_f32_e32 v137, s4, v137
	v_mul_f32_e32 v145, s4, v145
	v_mul_f32_e32 v138, s4, v138
	v_mul_f32_e32 v146, s4, v146
	v_mul_f32_e32 v139, s4, v139
	v_mul_f32_e32 v147, s4, v147
	v_mul_f32_e32 v140, s4, v140
	v_mul_f32_e32 v148, s4, v148
	v_mul_f32_e32 v141, s4, v141
	v_mul_f32_e32 v149, s4, v149
	v_cvt_pk_bf16_f32 v24, v134, v135
	v_cvt_pk_bf16_f32 v28, v142, v143
	v_cvt_pk_bf16_f32 v25, v136, v137
	v_cvt_pk_bf16_f32 v29, v144, v145
	v_cvt_pk_bf16_f32 v26, v138, v139
	v_cvt_pk_bf16_f32 v30, v146, v147
	v_cvt_pk_bf16_f32 v27, v140, v141
	v_cvt_pk_bf16_f32 v31, v148, v149
	s_add_u32 s0, s92, 0x0
	s_addc_u32 s1, s93, 0
	global_store_dwordx4 v0, v[24:27], s[0:1]
	global_store_dwordx4 v0, v[28:31], s[0:1] offset:64
	s_waitcnt vmcnt(22)
	v_lshlrev_b32_e32 v150, 16, v32
	v_lshlrev_b32_e32 v151, 16, v36
	v_mul_f32_e32 v152, v16, v151
	v_mul_f32_e32 v142, v16, v150
	v_fma_f32 v134, v8, v150, -v152
	v_fmac_f32_e32 v142, v8, v151
	v_and_b32_e32 v150, s5, v32
	v_and_b32_e32 v151, s5, v36
	v_mul_f32_e32 v152, v17, v151
	v_mul_f32_e32 v143, v17, v150
	v_fma_f32 v135, v9, v150, -v152
	v_fmac_f32_e32 v143, v9, v151
	v_lshlrev_b32_e32 v150, 16, v33
	v_lshlrev_b32_e32 v151, 16, v37
	v_mul_f32_e32 v152, v18, v151
	v_mul_f32_e32 v144, v18, v150
	v_fma_f32 v136, v10, v150, -v152
	v_fmac_f32_e32 v144, v10, v151
	v_and_b32_e32 v150, s5, v33
	v_and_b32_e32 v151, s5, v37
	v_mul_f32_e32 v152, v19, v151
	v_mul_f32_e32 v145, v19, v150
	v_fma_f32 v137, v11, v150, -v152
	v_fmac_f32_e32 v145, v11, v151
	v_lshlrev_b32_e32 v150, 16, v34
	v_lshlrev_b32_e32 v151, 16, v38
	v_mul_f32_e32 v152, v20, v151
	v_mul_f32_e32 v146, v20, v150
	v_fma_f32 v138, v12, v150, -v152
	v_fmac_f32_e32 v146, v12, v151
	v_and_b32_e32 v150, s5, v34
	v_and_b32_e32 v151, s5, v38
	v_mul_f32_e32 v152, v21, v151
	v_mul_f32_e32 v147, v21, v150
	v_fma_f32 v139, v13, v150, -v152
	v_fmac_f32_e32 v147, v13, v151
	v_lshlrev_b32_e32 v150, 16, v35
	v_lshlrev_b32_e32 v151, 16, v39
	v_mul_f32_e32 v152, v22, v151
	v_mul_f32_e32 v148, v22, v150
	v_fma_f32 v140, v14, v150, -v152
	v_fmac_f32_e32 v148, v14, v151
	v_and_b32_e32 v150, s5, v35
	v_and_b32_e32 v151, s5, v39
	v_mul_f32_e32 v152, v23, v151
	v_mul_f32_e32 v149, v23, v150
	v_fma_f32 v141, v15, v150, -v152
	v_fmac_f32_e32 v149, v15, v151
	v_mul_f32_e32 v134, s4, v134
	v_mul_f32_e32 v142, s4, v142
	v_mul_f32_e32 v135, s4, v135
	v_mul_f32_e32 v143, s4, v143
	v_mul_f32_e32 v136, s4, v136
	v_mul_f32_e32 v144, s4, v144
	v_mul_f32_e32 v137, s4, v137
	v_mul_f32_e32 v145, s4, v145
	v_mul_f32_e32 v138, s4, v138
	v_mul_f32_e32 v146, s4, v146
	v_mul_f32_e32 v139, s4, v139
	v_mul_f32_e32 v147, s4, v147
	v_mul_f32_e32 v140, s4, v140
	v_mul_f32_e32 v148, s4, v148
	v_mul_f32_e32 v141, s4, v141
	v_mul_f32_e32 v149, s4, v149
	v_cvt_pk_bf16_f32 v32, v134, v135
	v_cvt_pk_bf16_f32 v36, v142, v143
	v_cvt_pk_bf16_f32 v33, v136, v137
	v_cvt_pk_bf16_f32 v37, v144, v145
	v_cvt_pk_bf16_f32 v34, v138, v139
	v_cvt_pk_bf16_f32 v38, v146, v147
	v_cvt_pk_bf16_f32 v35, v140, v141
	v_cvt_pk_bf16_f32 v39, v148, v149
	s_add_u32 s0, s92, 0x800000
	s_addc_u32 s1, s93, 0
	global_store_dwordx4 v0, v[32:35], s[0:1]
	global_store_dwordx4 v0, v[36:39], s[0:1] offset:64
	s_waitcnt vmcnt(22)
	v_lshlrev_b32_e32 v150, 16, v40
	v_lshlrev_b32_e32 v151, 16, v44
	v_mul_f32_e32 v152, v16, v151
	v_mul_f32_e32 v142, v16, v150
	v_fma_f32 v134, v8, v150, -v152
	v_fmac_f32_e32 v142, v8, v151
	v_and_b32_e32 v150, s5, v40
	v_and_b32_e32 v151, s5, v44
	v_mul_f32_e32 v152, v17, v151
	v_mul_f32_e32 v143, v17, v150
	v_fma_f32 v135, v9, v150, -v152
	v_fmac_f32_e32 v143, v9, v151
	v_lshlrev_b32_e32 v150, 16, v41
	v_lshlrev_b32_e32 v151, 16, v45
	v_mul_f32_e32 v152, v18, v151
	v_mul_f32_e32 v144, v18, v150
	v_fma_f32 v136, v10, v150, -v152
	v_fmac_f32_e32 v144, v10, v151
	v_and_b32_e32 v150, s5, v41
	v_and_b32_e32 v151, s5, v45
	v_mul_f32_e32 v152, v19, v151
	v_mul_f32_e32 v145, v19, v150
	v_fma_f32 v137, v11, v150, -v152
	v_fmac_f32_e32 v145, v11, v151
	v_lshlrev_b32_e32 v150, 16, v42
	v_lshlrev_b32_e32 v151, 16, v46
	v_mul_f32_e32 v152, v20, v151
	v_mul_f32_e32 v146, v20, v150
	v_fma_f32 v138, v12, v150, -v152
	v_fmac_f32_e32 v146, v12, v151
	v_and_b32_e32 v150, s5, v42
	v_and_b32_e32 v151, s5, v46
	v_mul_f32_e32 v152, v21, v151
	v_mul_f32_e32 v147, v21, v150
	v_fma_f32 v139, v13, v150, -v152
	v_fmac_f32_e32 v147, v13, v151
	v_lshlrev_b32_e32 v150, 16, v43
	v_lshlrev_b32_e32 v151, 16, v47
	v_mul_f32_e32 v152, v22, v151
	v_mul_f32_e32 v148, v22, v150
	v_fma_f32 v140, v14, v150, -v152
	v_fmac_f32_e32 v148, v14, v151
	v_and_b32_e32 v150, s5, v43
	v_and_b32_e32 v151, s5, v47
	v_mul_f32_e32 v152, v23, v151
	v_mul_f32_e32 v149, v23, v150
	v_fma_f32 v141, v15, v150, -v152
	v_fmac_f32_e32 v149, v15, v151
	v_mul_f32_e32 v134, s4, v134
	v_mul_f32_e32 v142, s4, v142
	v_mul_f32_e32 v135, s4, v135
	v_mul_f32_e32 v143, s4, v143
	v_mul_f32_e32 v136, s4, v136
	v_mul_f32_e32 v144, s4, v144
	v_mul_f32_e32 v137, s4, v137
	v_mul_f32_e32 v145, s4, v145
	v_mul_f32_e32 v138, s4, v138
	v_mul_f32_e32 v146, s4, v146
	v_mul_f32_e32 v139, s4, v139
	v_mul_f32_e32 v147, s4, v147
	v_mul_f32_e32 v140, s4, v140
	v_mul_f32_e32 v148, s4, v148
	v_mul_f32_e32 v141, s4, v141
	v_mul_f32_e32 v149, s4, v149
	v_cvt_pk_bf16_f32 v40, v134, v135
	v_cvt_pk_bf16_f32 v44, v142, v143
	v_cvt_pk_bf16_f32 v41, v136, v137
	v_cvt_pk_bf16_f32 v45, v144, v145
	v_cvt_pk_bf16_f32 v42, v138, v139
	v_cvt_pk_bf16_f32 v46, v146, v147
	v_cvt_pk_bf16_f32 v43, v140, v141
	v_cvt_pk_bf16_f32 v47, v148, v149
	s_add_u32 s0, s92, 0x1000000
	s_addc_u32 s1, s93, 0
	global_store_dwordx4 v0, v[40:43], s[0:1]
	global_store_dwordx4 v0, v[44:47], s[0:1] offset:64
	s_waitcnt vmcnt(22)
	v_lshlrev_b32_e32 v150, 16, v48
	v_lshlrev_b32_e32 v151, 16, v52
	v_mul_f32_e32 v152, v16, v151
	v_mul_f32_e32 v142, v16, v150
	v_fma_f32 v134, v8, v150, -v152
	v_fmac_f32_e32 v142, v8, v151
	v_and_b32_e32 v150, s5, v48
	v_and_b32_e32 v151, s5, v52
	v_mul_f32_e32 v152, v17, v151
	v_mul_f32_e32 v143, v17, v150
	v_fma_f32 v135, v9, v150, -v152
	v_fmac_f32_e32 v143, v9, v151
	v_lshlrev_b32_e32 v150, 16, v49
	v_lshlrev_b32_e32 v151, 16, v53
	v_mul_f32_e32 v152, v18, v151
	v_mul_f32_e32 v144, v18, v150
	v_fma_f32 v136, v10, v150, -v152
	v_fmac_f32_e32 v144, v10, v151
	v_and_b32_e32 v150, s5, v49
	v_and_b32_e32 v151, s5, v53
	v_mul_f32_e32 v152, v19, v151
	v_mul_f32_e32 v145, v19, v150
	v_fma_f32 v137, v11, v150, -v152
	v_fmac_f32_e32 v145, v11, v151
	v_lshlrev_b32_e32 v150, 16, v50
	v_lshlrev_b32_e32 v151, 16, v54
	v_mul_f32_e32 v152, v20, v151
	v_mul_f32_e32 v146, v20, v150
	v_fma_f32 v138, v12, v150, -v152
	v_fmac_f32_e32 v146, v12, v151
	v_and_b32_e32 v150, s5, v50
	v_and_b32_e32 v151, s5, v54
	v_mul_f32_e32 v152, v21, v151
	v_mul_f32_e32 v147, v21, v150
	v_fma_f32 v139, v13, v150, -v152
	v_fmac_f32_e32 v147, v13, v151
	v_lshlrev_b32_e32 v150, 16, v51
	v_lshlrev_b32_e32 v151, 16, v55
	v_mul_f32_e32 v152, v22, v151
	v_mul_f32_e32 v148, v22, v150
	v_fma_f32 v140, v14, v150, -v152
	v_fmac_f32_e32 v148, v14, v151
	v_and_b32_e32 v150, s5, v51
	v_and_b32_e32 v151, s5, v55
	v_mul_f32_e32 v152, v23, v151
	v_mul_f32_e32 v149, v23, v150
	v_fma_f32 v141, v15, v150, -v152
	v_fmac_f32_e32 v149, v15, v151
	v_mul_f32_e32 v134, s4, v134
	v_mul_f32_e32 v142, s4, v142
	v_mul_f32_e32 v135, s4, v135
	v_mul_f32_e32 v143, s4, v143
	v_mul_f32_e32 v136, s4, v136
	v_mul_f32_e32 v144, s4, v144
	v_mul_f32_e32 v137, s4, v137
	v_mul_f32_e32 v145, s4, v145
	v_mul_f32_e32 v138, s4, v138
	v_mul_f32_e32 v146, s4, v146
	v_mul_f32_e32 v139, s4, v139
	v_mul_f32_e32 v147, s4, v147
	v_mul_f32_e32 v140, s4, v140
	v_mul_f32_e32 v148, s4, v148
	v_mul_f32_e32 v141, s4, v141
	v_mul_f32_e32 v149, s4, v149
	v_cvt_pk_bf16_f32 v48, v134, v135
	v_cvt_pk_bf16_f32 v52, v142, v143
	v_cvt_pk_bf16_f32 v49, v136, v137
	v_cvt_pk_bf16_f32 v53, v144, v145
	v_cvt_pk_bf16_f32 v50, v138, v139
	v_cvt_pk_bf16_f32 v54, v146, v147
	v_cvt_pk_bf16_f32 v51, v140, v141
	v_cvt_pk_bf16_f32 v55, v148, v149
	s_add_u32 s0, s92, 0x1800000
	s_addc_u32 s1, s93, 0
	global_store_dwordx4 v0, v[48:51], s[0:1]
	global_store_dwordx4 v0, v[52:55], s[0:1] offset:64
	s_waitcnt vmcnt(22)
	v_lshlrev_b32_e32 v150, 16, v56
	v_lshlrev_b32_e32 v151, 16, v60
	v_mul_f32_e32 v152, v16, v151
	v_mul_f32_e32 v142, v16, v150
	v_fma_f32 v134, v8, v150, -v152
	v_fmac_f32_e32 v142, v8, v151
	v_and_b32_e32 v150, s5, v56
	v_and_b32_e32 v151, s5, v60
	v_mul_f32_e32 v152, v17, v151
	v_mul_f32_e32 v143, v17, v150
	v_fma_f32 v135, v9, v150, -v152
	v_fmac_f32_e32 v143, v9, v151
	v_lshlrev_b32_e32 v150, 16, v57
	v_lshlrev_b32_e32 v151, 16, v61
	v_mul_f32_e32 v152, v18, v151
	v_mul_f32_e32 v144, v18, v150
	v_fma_f32 v136, v10, v150, -v152
	v_fmac_f32_e32 v144, v10, v151
	v_and_b32_e32 v150, s5, v57
	v_and_b32_e32 v151, s5, v61
	v_mul_f32_e32 v152, v19, v151
	v_mul_f32_e32 v145, v19, v150
	v_fma_f32 v137, v11, v150, -v152
	v_fmac_f32_e32 v145, v11, v151
	v_lshlrev_b32_e32 v150, 16, v58
	v_lshlrev_b32_e32 v151, 16, v62
	v_mul_f32_e32 v152, v20, v151
	v_mul_f32_e32 v146, v20, v150
	v_fma_f32 v138, v12, v150, -v152
	v_fmac_f32_e32 v146, v12, v151
	v_and_b32_e32 v150, s5, v58
	v_and_b32_e32 v151, s5, v62
	v_mul_f32_e32 v152, v21, v151
	v_mul_f32_e32 v147, v21, v150
	v_fma_f32 v139, v13, v150, -v152
	v_fmac_f32_e32 v147, v13, v151
	v_lshlrev_b32_e32 v150, 16, v59
	v_lshlrev_b32_e32 v151, 16, v63
	v_mul_f32_e32 v152, v22, v151
	v_mul_f32_e32 v148, v22, v150
	v_fma_f32 v140, v14, v150, -v152
	v_fmac_f32_e32 v148, v14, v151
	v_and_b32_e32 v150, s5, v59
	v_and_b32_e32 v151, s5, v63
	v_mul_f32_e32 v152, v23, v151
	v_mul_f32_e32 v149, v23, v150
	v_fma_f32 v141, v15, v150, -v152
	v_fmac_f32_e32 v149, v15, v151
	v_mul_f32_e32 v134, s4, v134
	v_mul_f32_e32 v142, s4, v142
	v_mul_f32_e32 v135, s4, v135
	v_mul_f32_e32 v143, s4, v143
	v_mul_f32_e32 v136, s4, v136
	v_mul_f32_e32 v144, s4, v144
	v_mul_f32_e32 v137, s4, v137
	v_mul_f32_e32 v145, s4, v145
	v_mul_f32_e32 v138, s4, v138
	v_mul_f32_e32 v146, s4, v146
	v_mul_f32_e32 v139, s4, v139
	v_mul_f32_e32 v147, s4, v147
	v_mul_f32_e32 v140, s4, v140
	v_mul_f32_e32 v148, s4, v148
	v_mul_f32_e32 v141, s4, v141
	v_mul_f32_e32 v149, s4, v149
	v_cvt_pk_bf16_f32 v56, v134, v135
	v_cvt_pk_bf16_f32 v60, v142, v143
	v_cvt_pk_bf16_f32 v57, v136, v137
	v_cvt_pk_bf16_f32 v61, v144, v145
	v_cvt_pk_bf16_f32 v58, v138, v139
	v_cvt_pk_bf16_f32 v62, v146, v147
	v_cvt_pk_bf16_f32 v59, v140, v141
	v_cvt_pk_bf16_f32 v63, v148, v149
	s_add_u32 s0, s92, 0x2000000
	s_addc_u32 s1, s93, 0
	global_store_dwordx4 v0, v[56:59], s[0:1]
	global_store_dwordx4 v0, v[60:63], s[0:1] offset:64
	s_waitcnt vmcnt(22)
	v_lshlrev_b32_e32 v150, 16, v64
	v_lshlrev_b32_e32 v151, 16, v68
	v_mul_f32_e32 v152, v16, v151
	v_mul_f32_e32 v142, v16, v150
	v_fma_f32 v134, v8, v150, -v152
	v_fmac_f32_e32 v142, v8, v151
	v_and_b32_e32 v150, s5, v64
	v_and_b32_e32 v151, s5, v68
	v_mul_f32_e32 v152, v17, v151
	v_mul_f32_e32 v143, v17, v150
	v_fma_f32 v135, v9, v150, -v152
	v_fmac_f32_e32 v143, v9, v151
	v_lshlrev_b32_e32 v150, 16, v65
	v_lshlrev_b32_e32 v151, 16, v69
	v_mul_f32_e32 v152, v18, v151
	v_mul_f32_e32 v144, v18, v150
	v_fma_f32 v136, v10, v150, -v152
	v_fmac_f32_e32 v144, v10, v151
	v_and_b32_e32 v150, s5, v65
	v_and_b32_e32 v151, s5, v69
	v_mul_f32_e32 v152, v19, v151
	v_mul_f32_e32 v145, v19, v150
	v_fma_f32 v137, v11, v150, -v152
	v_fmac_f32_e32 v145, v11, v151
	v_lshlrev_b32_e32 v150, 16, v66
	v_lshlrev_b32_e32 v151, 16, v70
	v_mul_f32_e32 v152, v20, v151
	v_mul_f32_e32 v146, v20, v150
	v_fma_f32 v138, v12, v150, -v152
	v_fmac_f32_e32 v146, v12, v151
	v_and_b32_e32 v150, s5, v66
	v_and_b32_e32 v151, s5, v70
	v_mul_f32_e32 v152, v21, v151
	v_mul_f32_e32 v147, v21, v150
	v_fma_f32 v139, v13, v150, -v152
	v_fmac_f32_e32 v147, v13, v151
	v_lshlrev_b32_e32 v150, 16, v67
	v_lshlrev_b32_e32 v151, 16, v71
	v_mul_f32_e32 v152, v22, v151
	v_mul_f32_e32 v148, v22, v150
	v_fma_f32 v140, v14, v150, -v152
	v_fmac_f32_e32 v148, v14, v151
	v_and_b32_e32 v150, s5, v67
	v_and_b32_e32 v151, s5, v71
	v_mul_f32_e32 v152, v23, v151
	v_mul_f32_e32 v149, v23, v150
	v_fma_f32 v141, v15, v150, -v152
	v_fmac_f32_e32 v149, v15, v151
	v_mul_f32_e32 v134, s4, v134
	v_mul_f32_e32 v142, s4, v142
	v_mul_f32_e32 v135, s4, v135
	v_mul_f32_e32 v143, s4, v143
	v_mul_f32_e32 v136, s4, v136
	v_mul_f32_e32 v144, s4, v144
	v_mul_f32_e32 v137, s4, v137
	v_mul_f32_e32 v145, s4, v145
	v_mul_f32_e32 v138, s4, v138
	v_mul_f32_e32 v146, s4, v146
	v_mul_f32_e32 v139, s4, v139
	v_mul_f32_e32 v147, s4, v147
	v_mul_f32_e32 v140, s4, v140
	v_mul_f32_e32 v148, s4, v148
	v_mul_f32_e32 v141, s4, v141
	v_mul_f32_e32 v149, s4, v149
	v_cvt_pk_bf16_f32 v64, v134, v135
	v_cvt_pk_bf16_f32 v68, v142, v143
	v_cvt_pk_bf16_f32 v65, v136, v137
	v_cvt_pk_bf16_f32 v69, v144, v145
	v_cvt_pk_bf16_f32 v66, v138, v139
	v_cvt_pk_bf16_f32 v70, v146, v147
	v_cvt_pk_bf16_f32 v67, v140, v141
	v_cvt_pk_bf16_f32 v71, v148, v149
	s_add_u32 s0, s92, 0x2800000
	s_addc_u32 s1, s93, 0
	global_store_dwordx4 v0, v[64:67], s[0:1]
	global_store_dwordx4 v0, v[68:71], s[0:1] offset:64
	s_waitcnt vmcnt(22)
	v_lshlrev_b32_e32 v150, 16, v72
	v_lshlrev_b32_e32 v151, 16, v76
	v_mul_f32_e32 v152, v16, v151
	v_mul_f32_e32 v142, v16, v150
	v_fma_f32 v134, v8, v150, -v152
	v_fmac_f32_e32 v142, v8, v151
	v_and_b32_e32 v150, s5, v72
	v_and_b32_e32 v151, s5, v76
	v_mul_f32_e32 v152, v17, v151
	v_mul_f32_e32 v143, v17, v150
	v_fma_f32 v135, v9, v150, -v152
	v_fmac_f32_e32 v143, v9, v151
	v_lshlrev_b32_e32 v150, 16, v73
	v_lshlrev_b32_e32 v151, 16, v77
	v_mul_f32_e32 v152, v18, v151
	v_mul_f32_e32 v144, v18, v150
	v_fma_f32 v136, v10, v150, -v152
	v_fmac_f32_e32 v144, v10, v151
	v_and_b32_e32 v150, s5, v73
	v_and_b32_e32 v151, s5, v77
	v_mul_f32_e32 v152, v19, v151
	v_mul_f32_e32 v145, v19, v150
	v_fma_f32 v137, v11, v150, -v152
	v_fmac_f32_e32 v145, v11, v151
	v_lshlrev_b32_e32 v150, 16, v74
	v_lshlrev_b32_e32 v151, 16, v78
	v_mul_f32_e32 v152, v20, v151
	v_mul_f32_e32 v146, v20, v150
	v_fma_f32 v138, v12, v150, -v152
	v_fmac_f32_e32 v146, v12, v151
	v_and_b32_e32 v150, s5, v74
	v_and_b32_e32 v151, s5, v78
	v_mul_f32_e32 v152, v21, v151
	v_mul_f32_e32 v147, v21, v150
	v_fma_f32 v139, v13, v150, -v152
	v_fmac_f32_e32 v147, v13, v151
	v_lshlrev_b32_e32 v150, 16, v75
	v_lshlrev_b32_e32 v151, 16, v79
	v_mul_f32_e32 v152, v22, v151
	v_mul_f32_e32 v148, v22, v150
	v_fma_f32 v140, v14, v150, -v152
	v_fmac_f32_e32 v148, v14, v151
	v_and_b32_e32 v150, s5, v75
	v_and_b32_e32 v151, s5, v79
	v_mul_f32_e32 v152, v23, v151
	v_mul_f32_e32 v149, v23, v150
	v_fma_f32 v141, v15, v150, -v152
	v_fmac_f32_e32 v149, v15, v151
	v_mul_f32_e32 v134, s4, v134
	v_mul_f32_e32 v142, s4, v142
	v_mul_f32_e32 v135, s4, v135
	v_mul_f32_e32 v143, s4, v143
	v_mul_f32_e32 v136, s4, v136
	v_mul_f32_e32 v144, s4, v144
	v_mul_f32_e32 v137, s4, v137
	v_mul_f32_e32 v145, s4, v145
	v_mul_f32_e32 v138, s4, v138
	v_mul_f32_e32 v146, s4, v146
	v_mul_f32_e32 v139, s4, v139
	v_mul_f32_e32 v147, s4, v147
	v_mul_f32_e32 v140, s4, v140
	v_mul_f32_e32 v148, s4, v148
	v_mul_f32_e32 v141, s4, v141
	v_mul_f32_e32 v149, s4, v149
	v_cvt_pk_bf16_f32 v72, v134, v135
	v_cvt_pk_bf16_f32 v76, v142, v143
	v_cvt_pk_bf16_f32 v73, v136, v137
	v_cvt_pk_bf16_f32 v77, v144, v145
	v_cvt_pk_bf16_f32 v74, v138, v139
	v_cvt_pk_bf16_f32 v78, v146, v147
	v_cvt_pk_bf16_f32 v75, v140, v141
	v_cvt_pk_bf16_f32 v79, v148, v149
	s_add_u32 s0, s92, 0x3000000
	s_addc_u32 s1, s93, 0
	global_store_dwordx4 v0, v[72:75], s[0:1]
	global_store_dwordx4 v0, v[76:79], s[0:1] offset:64
	s_waitcnt vmcnt(22)
	v_lshlrev_b32_e32 v150, 16, v80
	v_lshlrev_b32_e32 v151, 16, v84
	v_mul_f32_e32 v152, v16, v151
	v_mul_f32_e32 v142, v16, v150
	v_fma_f32 v134, v8, v150, -v152
	v_fmac_f32_e32 v142, v8, v151
	v_and_b32_e32 v150, s5, v80
	v_and_b32_e32 v151, s5, v84
	v_mul_f32_e32 v152, v17, v151
	v_mul_f32_e32 v143, v17, v150
	v_fma_f32 v135, v9, v150, -v152
	v_fmac_f32_e32 v143, v9, v151
	v_lshlrev_b32_e32 v150, 16, v81
	v_lshlrev_b32_e32 v151, 16, v85
	v_mul_f32_e32 v152, v18, v151
	v_mul_f32_e32 v144, v18, v150
	v_fma_f32 v136, v10, v150, -v152
	v_fmac_f32_e32 v144, v10, v151
	v_and_b32_e32 v150, s5, v81
	v_and_b32_e32 v151, s5, v85
	v_mul_f32_e32 v152, v19, v151
	v_mul_f32_e32 v145, v19, v150
	v_fma_f32 v137, v11, v150, -v152
	v_fmac_f32_e32 v145, v11, v151
	v_lshlrev_b32_e32 v150, 16, v82
	v_lshlrev_b32_e32 v151, 16, v86
	v_mul_f32_e32 v152, v20, v151
	v_mul_f32_e32 v146, v20, v150
	v_fma_f32 v138, v12, v150, -v152
	v_fmac_f32_e32 v146, v12, v151
	v_and_b32_e32 v150, s5, v82
	v_and_b32_e32 v151, s5, v86
	v_mul_f32_e32 v152, v21, v151
	v_mul_f32_e32 v147, v21, v150
	v_fma_f32 v139, v13, v150, -v152
	v_fmac_f32_e32 v147, v13, v151
	v_lshlrev_b32_e32 v150, 16, v83
	v_lshlrev_b32_e32 v151, 16, v87
	v_mul_f32_e32 v152, v22, v151
	v_mul_f32_e32 v148, v22, v150
	v_fma_f32 v140, v14, v150, -v152
	v_fmac_f32_e32 v148, v14, v151
	v_and_b32_e32 v150, s5, v83
	v_and_b32_e32 v151, s5, v87
	v_mul_f32_e32 v152, v23, v151
	v_mul_f32_e32 v149, v23, v150
	v_fma_f32 v141, v15, v150, -v152
	v_fmac_f32_e32 v149, v15, v151
	v_mul_f32_e32 v134, s4, v134
	v_mul_f32_e32 v142, s4, v142
	v_mul_f32_e32 v135, s4, v135
	v_mul_f32_e32 v143, s4, v143
	v_mul_f32_e32 v136, s4, v136
	v_mul_f32_e32 v144, s4, v144
	v_mul_f32_e32 v137, s4, v137
	v_mul_f32_e32 v145, s4, v145
	v_mul_f32_e32 v138, s4, v138
	v_mul_f32_e32 v146, s4, v146
	v_mul_f32_e32 v139, s4, v139
	v_mul_f32_e32 v147, s4, v147
	v_mul_f32_e32 v140, s4, v140
	v_mul_f32_e32 v148, s4, v148
	v_mul_f32_e32 v141, s4, v141
	v_mul_f32_e32 v149, s4, v149
	v_cvt_pk_bf16_f32 v80, v134, v135
	v_cvt_pk_bf16_f32 v84, v142, v143
	v_cvt_pk_bf16_f32 v81, v136, v137
	v_cvt_pk_bf16_f32 v85, v144, v145
	v_cvt_pk_bf16_f32 v82, v138, v139
	v_cvt_pk_bf16_f32 v86, v146, v147
	v_cvt_pk_bf16_f32 v83, v140, v141
	v_cvt_pk_bf16_f32 v87, v148, v149
	s_add_u32 s0, s92, 0x3800000
	s_addc_u32 s1, s93, 0
	global_store_dwordx4 v0, v[80:83], s[0:1]
	global_store_dwordx4 v0, v[84:87], s[0:1] offset:64
	s_waitcnt vmcnt(22)
	s_mov_b32 s4, 1.0
	v_lshlrev_b32_e32 v150, 16, v88
	v_lshlrev_b32_e32 v151, 16, v92
	v_mul_f32_e32 v152, v16, v151
	v_mul_f32_e32 v142, v16, v150
	v_fma_f32 v134, v8, v150, -v152
	v_fmac_f32_e32 v142, v8, v151
	v_and_b32_e32 v150, s5, v88
	v_and_b32_e32 v151, s5, v92
	v_mul_f32_e32 v152, v17, v151
	v_mul_f32_e32 v143, v17, v150
	v_fma_f32 v135, v9, v150, -v152
	v_fmac_f32_e32 v143, v9, v151
	v_lshlrev_b32_e32 v150, 16, v89
	v_lshlrev_b32_e32 v151, 16, v93
	v_mul_f32_e32 v152, v18, v151
	v_mul_f32_e32 v144, v18, v150
	v_fma_f32 v136, v10, v150, -v152
	v_fmac_f32_e32 v144, v10, v151
	v_and_b32_e32 v150, s5, v89
	v_and_b32_e32 v151, s5, v93
	v_mul_f32_e32 v152, v19, v151
	v_mul_f32_e32 v145, v19, v150
	v_fma_f32 v137, v11, v150, -v152
	v_fmac_f32_e32 v145, v11, v151
	v_lshlrev_b32_e32 v150, 16, v90
	v_lshlrev_b32_e32 v151, 16, v94
	v_mul_f32_e32 v152, v20, v151
	v_mul_f32_e32 v146, v20, v150
	v_fma_f32 v138, v12, v150, -v152
	v_fmac_f32_e32 v146, v12, v151
	v_and_b32_e32 v150, s5, v90
	v_and_b32_e32 v151, s5, v94
	v_mul_f32_e32 v152, v21, v151
	v_mul_f32_e32 v147, v21, v150
	v_fma_f32 v139, v13, v150, -v152
	v_fmac_f32_e32 v147, v13, v151
	v_lshlrev_b32_e32 v150, 16, v91
	v_lshlrev_b32_e32 v151, 16, v95
	v_mul_f32_e32 v152, v22, v151
	v_mul_f32_e32 v148, v22, v150
	v_fma_f32 v140, v14, v150, -v152
	v_fmac_f32_e32 v148, v14, v151
	v_and_b32_e32 v150, s5, v91
	v_and_b32_e32 v151, s5, v95
	v_mul_f32_e32 v152, v23, v151
	v_mul_f32_e32 v149, v23, v150
	v_fma_f32 v141, v15, v150, -v152
	v_fmac_f32_e32 v149, v15, v151
	v_mul_f32_e32 v134, s4, v134
	v_mul_f32_e32 v142, s4, v142
	v_mul_f32_e32 v135, s4, v135
	v_mul_f32_e32 v143, s4, v143
	v_mul_f32_e32 v136, s4, v136
	v_mul_f32_e32 v144, s4, v144
	v_mul_f32_e32 v137, s4, v137
	v_mul_f32_e32 v145, s4, v145
	v_mul_f32_e32 v138, s4, v138
	v_mul_f32_e32 v146, s4, v146
	v_mul_f32_e32 v139, s4, v139
	v_mul_f32_e32 v147, s4, v147
	v_mul_f32_e32 v140, s4, v140
	v_mul_f32_e32 v148, s4, v148
	v_mul_f32_e32 v141, s4, v141
	v_mul_f32_e32 v149, s4, v149
	v_cvt_pk_bf16_f32 v88, v134, v135
	v_cvt_pk_bf16_f32 v92, v142, v143
	v_cvt_pk_bf16_f32 v89, v136, v137
	v_cvt_pk_bf16_f32 v93, v144, v145
	v_cvt_pk_bf16_f32 v90, v138, v139
	v_cvt_pk_bf16_f32 v94, v146, v147
	v_cvt_pk_bf16_f32 v91, v140, v141
	v_cvt_pk_bf16_f32 v95, v148, v149
	s_add_u32 s0, s92, 0x6000000
	s_addc_u32 s1, s93, 0
	global_store_dwordx4 v0, v[88:91], s[0:1]
	global_store_dwordx4 v0, v[92:95], s[0:1] offset:64
	s_waitcnt vmcnt(22)
	v_lshlrev_b32_e32 v150, 16, v96
	v_lshlrev_b32_e32 v151, 16, v100
	v_mul_f32_e32 v152, v16, v151
	v_mul_f32_e32 v142, v16, v150
	v_fma_f32 v134, v8, v150, -v152
	v_fmac_f32_e32 v142, v8, v151
	v_and_b32_e32 v150, s5, v96
	v_and_b32_e32 v151, s5, v100
	v_mul_f32_e32 v152, v17, v151
	v_mul_f32_e32 v143, v17, v150
	v_fma_f32 v135, v9, v150, -v152
	v_fmac_f32_e32 v143, v9, v151
	v_lshlrev_b32_e32 v150, 16, v97
	v_lshlrev_b32_e32 v151, 16, v101
	v_mul_f32_e32 v152, v18, v151
	v_mul_f32_e32 v144, v18, v150
	v_fma_f32 v136, v10, v150, -v152
	v_fmac_f32_e32 v144, v10, v151
	v_and_b32_e32 v150, s5, v97
	v_and_b32_e32 v151, s5, v101
	v_mul_f32_e32 v152, v19, v151
	v_mul_f32_e32 v145, v19, v150
	v_fma_f32 v137, v11, v150, -v152
	v_fmac_f32_e32 v145, v11, v151
	v_lshlrev_b32_e32 v150, 16, v98
	v_lshlrev_b32_e32 v151, 16, v102
	v_mul_f32_e32 v152, v20, v151
	v_mul_f32_e32 v146, v20, v150
	v_fma_f32 v138, v12, v150, -v152
	v_fmac_f32_e32 v146, v12, v151
	v_and_b32_e32 v150, s5, v98
	v_and_b32_e32 v151, s5, v102
	v_mul_f32_e32 v152, v21, v151
	v_mul_f32_e32 v147, v21, v150
	v_fma_f32 v139, v13, v150, -v152
	v_fmac_f32_e32 v147, v13, v151
	v_lshlrev_b32_e32 v150, 16, v99
	v_lshlrev_b32_e32 v151, 16, v103
	v_mul_f32_e32 v152, v22, v151
	v_mul_f32_e32 v148, v22, v150
	v_fma_f32 v140, v14, v150, -v152
	v_fmac_f32_e32 v148, v14, v151
	v_and_b32_e32 v150, s5, v99
	v_and_b32_e32 v151, s5, v103
	v_mul_f32_e32 v152, v23, v151
	v_mul_f32_e32 v149, v23, v150
	v_fma_f32 v141, v15, v150, -v152
	v_fmac_f32_e32 v149, v15, v151
	v_mul_f32_e32 v134, s4, v134
	v_mul_f32_e32 v142, s4, v142
	v_mul_f32_e32 v135, s4, v135
	v_mul_f32_e32 v143, s4, v143
	v_mul_f32_e32 v136, s4, v136
	v_mul_f32_e32 v144, s4, v144
	v_mul_f32_e32 v137, s4, v137
	v_mul_f32_e32 v145, s4, v145
	v_mul_f32_e32 v138, s4, v138
	v_mul_f32_e32 v146, s4, v146
	v_mul_f32_e32 v139, s4, v139
	v_mul_f32_e32 v147, s4, v147
	v_mul_f32_e32 v140, s4, v140
	v_mul_f32_e32 v148, s4, v148
	v_mul_f32_e32 v141, s4, v141
	v_mul_f32_e32 v149, s4, v149
	v_cvt_pk_bf16_f32 v96, v134, v135
	v_cvt_pk_bf16_f32 v100, v142, v143
	v_cvt_pk_bf16_f32 v97, v136, v137
	v_cvt_pk_bf16_f32 v101, v144, v145
	v_cvt_pk_bf16_f32 v98, v138, v139
	v_cvt_pk_bf16_f32 v102, v146, v147
	v_cvt_pk_bf16_f32 v99, v140, v141
	v_cvt_pk_bf16_f32 v103, v148, v149
	s_add_u32 s0, s92, 0x6800000
	s_addc_u32 s1, s93, 0
	global_store_dwordx4 v0, v[96:99], s[0:1]
	global_store_dwordx4 v0, v[100:103], s[0:1] offset:64
	s_waitcnt vmcnt(22)
	v_lshlrev_b32_e32 v150, 16, v104
	v_lshlrev_b32_e32 v151, 16, v108
	v_mul_f32_e32 v152, v16, v151
	v_mul_f32_e32 v142, v16, v150
	v_fma_f32 v134, v8, v150, -v152
	v_fmac_f32_e32 v142, v8, v151
	v_and_b32_e32 v150, s5, v104
	v_and_b32_e32 v151, s5, v108
	v_mul_f32_e32 v152, v17, v151
	v_mul_f32_e32 v143, v17, v150
	v_fma_f32 v135, v9, v150, -v152
	v_fmac_f32_e32 v143, v9, v151
	v_lshlrev_b32_e32 v150, 16, v105
	v_lshlrev_b32_e32 v151, 16, v109
	v_mul_f32_e32 v152, v18, v151
	v_mul_f32_e32 v144, v18, v150
	v_fma_f32 v136, v10, v150, -v152
	v_fmac_f32_e32 v144, v10, v151
	v_and_b32_e32 v150, s5, v105
	v_and_b32_e32 v151, s5, v109
	v_mul_f32_e32 v152, v19, v151
	v_mul_f32_e32 v145, v19, v150
	v_fma_f32 v137, v11, v150, -v152
	v_fmac_f32_e32 v145, v11, v151
	v_lshlrev_b32_e32 v150, 16, v106
	v_lshlrev_b32_e32 v151, 16, v110
	v_mul_f32_e32 v152, v20, v151
	v_mul_f32_e32 v146, v20, v150
	v_fma_f32 v138, v12, v150, -v152
	v_fmac_f32_e32 v146, v12, v151
	v_and_b32_e32 v150, s5, v106
	v_and_b32_e32 v151, s5, v110
	v_mul_f32_e32 v152, v21, v151
	v_mul_f32_e32 v147, v21, v150
	v_fma_f32 v139, v13, v150, -v152
	v_fmac_f32_e32 v147, v13, v151
	v_lshlrev_b32_e32 v150, 16, v107
	v_lshlrev_b32_e32 v151, 16, v111
	v_mul_f32_e32 v152, v22, v151
	v_mul_f32_e32 v148, v22, v150
	v_fma_f32 v140, v14, v150, -v152
	v_fmac_f32_e32 v148, v14, v151
	v_and_b32_e32 v150, s5, v107
	v_and_b32_e32 v151, s5, v111
	v_mul_f32_e32 v152, v23, v151
	v_mul_f32_e32 v149, v23, v150
	v_fma_f32 v141, v15, v150, -v152
	v_fmac_f32_e32 v149, v15, v151
	v_mul_f32_e32 v134, s4, v134
	v_mul_f32_e32 v142, s4, v142
	v_mul_f32_e32 v135, s4, v135
	v_mul_f32_e32 v143, s4, v143
	v_mul_f32_e32 v136, s4, v136
	v_mul_f32_e32 v144, s4, v144
	v_mul_f32_e32 v137, s4, v137
	v_mul_f32_e32 v145, s4, v145
	v_mul_f32_e32 v138, s4, v138
	v_mul_f32_e32 v146, s4, v146
	v_mul_f32_e32 v139, s4, v139
	v_mul_f32_e32 v147, s4, v147
	v_mul_f32_e32 v140, s4, v140
	v_mul_f32_e32 v148, s4, v148
	v_mul_f32_e32 v141, s4, v141
	v_mul_f32_e32 v149, s4, v149
	v_cvt_pk_bf16_f32 v104, v134, v135
	v_cvt_pk_bf16_f32 v108, v142, v143
	v_cvt_pk_bf16_f32 v105, v136, v137
	v_cvt_pk_bf16_f32 v109, v144, v145
	v_cvt_pk_bf16_f32 v106, v138, v139
	v_cvt_pk_bf16_f32 v110, v146, v147
	v_cvt_pk_bf16_f32 v107, v140, v141
	v_cvt_pk_bf16_f32 v111, v148, v149
	s_add_u32 s0, s92, 0x7000000
	s_addc_u32 s1, s93, 0
	global_store_dwordx4 v0, v[104:107], s[0:1]
	global_store_dwordx4 v0, v[108:111], s[0:1] offset:64
	s_waitcnt vmcnt(22)
	v_lshlrev_b32_e32 v150, 16, v112
	v_lshlrev_b32_e32 v151, 16, v116
	v_mul_f32_e32 v152, v16, v151
	v_mul_f32_e32 v142, v16, v150
	v_fma_f32 v134, v8, v150, -v152
	v_fmac_f32_e32 v142, v8, v151
	v_and_b32_e32 v150, s5, v112
	v_and_b32_e32 v151, s5, v116
	v_mul_f32_e32 v152, v17, v151
	v_mul_f32_e32 v143, v17, v150
	v_fma_f32 v135, v9, v150, -v152
	v_fmac_f32_e32 v143, v9, v151
	v_lshlrev_b32_e32 v150, 16, v113
	v_lshlrev_b32_e32 v151, 16, v117
	v_mul_f32_e32 v152, v18, v151
	v_mul_f32_e32 v144, v18, v150
	v_fma_f32 v136, v10, v150, -v152
	v_fmac_f32_e32 v144, v10, v151
	v_and_b32_e32 v150, s5, v113
	v_and_b32_e32 v151, s5, v117
	v_mul_f32_e32 v152, v19, v151
	v_mul_f32_e32 v145, v19, v150
	v_fma_f32 v137, v11, v150, -v152
	v_fmac_f32_e32 v145, v11, v151
	v_lshlrev_b32_e32 v150, 16, v114
	v_lshlrev_b32_e32 v151, 16, v118
	v_mul_f32_e32 v152, v20, v151
	v_mul_f32_e32 v146, v20, v150
	v_fma_f32 v138, v12, v150, -v152
	v_fmac_f32_e32 v146, v12, v151
	v_and_b32_e32 v150, s5, v114
	v_and_b32_e32 v151, s5, v118
	v_mul_f32_e32 v152, v21, v151
	v_mul_f32_e32 v147, v21, v150
	v_fma_f32 v139, v13, v150, -v152
	v_fmac_f32_e32 v147, v13, v151
	v_lshlrev_b32_e32 v150, 16, v115
	v_lshlrev_b32_e32 v151, 16, v119
	v_mul_f32_e32 v152, v22, v151
	v_mul_f32_e32 v148, v22, v150
	v_fma_f32 v140, v14, v150, -v152
	v_fmac_f32_e32 v148, v14, v151
	v_and_b32_e32 v150, s5, v115
	v_and_b32_e32 v151, s5, v119
	v_mul_f32_e32 v152, v23, v151
	v_mul_f32_e32 v149, v23, v150
	v_fma_f32 v141, v15, v150, -v152
	v_fmac_f32_e32 v149, v15, v151
	v_mul_f32_e32 v134, s4, v134
	v_mul_f32_e32 v142, s4, v142
	v_mul_f32_e32 v135, s4, v135
	v_mul_f32_e32 v143, s4, v143
	v_mul_f32_e32 v136, s4, v136
	v_mul_f32_e32 v144, s4, v144
	v_mul_f32_e32 v137, s4, v137
	v_mul_f32_e32 v145, s4, v145
	v_mul_f32_e32 v138, s4, v138
	v_mul_f32_e32 v146, s4, v146
	v_mul_f32_e32 v139, s4, v139
	v_mul_f32_e32 v147, s4, v147
	v_mul_f32_e32 v140, s4, v140
	v_mul_f32_e32 v148, s4, v148
	v_mul_f32_e32 v141, s4, v141
	v_mul_f32_e32 v149, s4, v149
	v_cvt_pk_bf16_f32 v112, v134, v135
	v_cvt_pk_bf16_f32 v116, v142, v143
	v_cvt_pk_bf16_f32 v113, v136, v137
	v_cvt_pk_bf16_f32 v117, v144, v145
	v_cvt_pk_bf16_f32 v114, v138, v139
	v_cvt_pk_bf16_f32 v118, v146, v147
	v_cvt_pk_bf16_f32 v115, v140, v141
	v_cvt_pk_bf16_f32 v119, v148, v149
	s_add_u32 s0, s92, 0x7800000
	s_addc_u32 s1, s93, 0
	global_store_dwordx4 v0, v[112:115], s[0:1]
	global_store_dwordx4 v0, v[116:119], s[0:1] offset:64
